# rms
# speedup vs baseline: 1.0099x; 1.0099x over previous
; DI unsigned cvtpk(float lo, float hi) { typedef float f2 __attribute__((ext_vector_type(2))); typedef __bf16 b2 __attribute__((ext_vector_type(2))); f2 v = {lo, hi}; b2 b = __builtin_convertvector(v, b2); return __builtin_bit_cast(unsigned, b); }
; DI void rms_row_bf16(const float* xrow, const float* gam, bf16* orow, int lane) {
;     f32x4 v[8]; float ss = 0.f;
; #pragma unroll
;     for (int j = 0; j < 8; ++j) { v[j] = ((const f32x4*)xrow)[lane + 64 * j]; ss += (v[j].x * v[j].x + v[j].y * v[j].y) + (v[j].z * v[j].z + v[j].w * v[j].w); }
;     const float rinv = rsqrtf(wave_sum(ss, lane) * (1.f / DM) + 1e-6f);
; #pragma unroll
;     for (int j = 0; j < 8; ++j) { const f32x4 g = ((const f32x4*)gam)[lane + 64 * j]; v2u w; w.x = cvtpk(v[j].x * rinv * g.x, v[j].y * rinv * g.y); w.y = cvtpk(v[j].z * rinv * g.z, v[j].w * rinv * g.w); ((v2u*)orow)[lane + 64 * j] = w; }
; }
.LBB0_38:
	global_load_dwordx4 v[128:131], v[38:39], off
	global_load_dwordx4 v[132:135], v[38:39], off offset:1024
	global_load_dwordx4 v[136:139], v[38:39], off offset:2048
	global_load_dwordx4 v[140:143], v[38:39], off offset:3072
	global_load_dwordx4 v[144:147], v[40:41], off
	global_load_dwordx4 v[148:151], v[40:41], off offset:1024
	global_load_dwordx4 v[152:155], v[40:41], off offset:2048
	global_load_dwordx4 v[156:159], v[40:41], off offset:3072
	global_load_dwordx4 v[96:99], v[50:51], off offset:-4096
	global_load_dwordx4 v[100:103], v[50:51], off offset:-3072
	global_load_dwordx4 v[104:107], v[50:51], off offset:-2048
	global_load_dwordx4 v[108:111], v[50:51], off offset:-1024
	global_load_dwordx4 v[112:115], v[50:51], off offset:0
	global_load_dwordx4 v[116:119], v[50:51], off offset:1024
	global_load_dwordx4 v[120:123], v[50:51], off offset:2048
	global_load_dwordx4 v[124:127], v[50:51], off offset:3072
	s_waitcnt vmcnt(0)
.Lrms_a_loop:
	s_waitcnt vmcnt(8)
	v_mov_b32_e32 v64, v96
	v_mov_b32_e32 v65, v97
	v_mov_b32_e32 v66, v98
	v_mov_b32_e32 v67, v99
	v_mov_b32_e32 v68, v100
	v_mov_b32_e32 v69, v101
	v_mov_b32_e32 v70, v102
	v_mov_b32_e32 v71, v103
	v_mov_b32_e32 v72, v104
	v_mov_b32_e32 v73, v105
	v_mov_b32_e32 v74, v106
	v_mov_b32_e32 v75, v107
	v_mov_b32_e32 v76, v108
	v_mov_b32_e32 v77, v109
	v_mov_b32_e32 v78, v110
	v_mov_b32_e32 v79, v111
	v_mov_b32_e32 v80, v112
	v_mov_b32_e32 v81, v113
	v_mov_b32_e32 v82, v114
	v_mov_b32_e32 v83, v115
	v_mov_b32_e32 v84, v116
	v_mov_b32_e32 v85, v117
	v_mov_b32_e32 v86, v118
	v_mov_b32_e32 v87, v119
	v_mov_b32_e32 v88, v120
	v_mov_b32_e32 v89, v121
	v_mov_b32_e32 v90, v122
	v_mov_b32_e32 v91, v123
	v_mov_b32_e32 v92, v124
	v_mov_b32_e32 v93, v125
	v_mov_b32_e32 v94, v126
	v_mov_b32_e32 v95, v127
	s_add_i32 s6, s6, s30
	s_cmpk_gt_i32 s6, 0x3fff
	s_cbranch_scc1 .Lrms_a_nopf
	v_lshl_add_u64 v[50:51], v[50:51], 0, s[60:61]
	global_load_dwordx4 v[96:99], v[50:51], off offset:-4096
	global_load_dwordx4 v[100:103], v[50:51], off offset:-3072
	global_load_dwordx4 v[104:107], v[50:51], off offset:-2048
	global_load_dwordx4 v[108:111], v[50:51], off offset:-1024
	global_load_dwordx4 v[112:115], v[50:51], off offset:0
	global_load_dwordx4 v[116:119], v[50:51], off offset:1024
	global_load_dwordx4 v[120:123], v[50:51], off offset:2048
	global_load_dwordx4 v[124:127], v[50:51], off offset:3072
; DI unsigned cvtpk(float lo, float hi) { typedef float f2 __attribute__((ext_vector_type(2))); typedef __bf16 b2 __attribute__((ext_vector_type(2))); f2 v = {lo, hi}; b2 b = __builtin_convertvector(v, b2); return __builtin_bit_cast(unsigned, b); }
; DI void rms_row_bf16(const float* xrow, const float* gam, bf16* orow, int lane) {
;     f32x4 v[8]; float ss = 0.f;
; #pragma unroll
;     for (int j = 0; j < 8; ++j) { v[j] = ((const f32x4*)xrow)[lane + 64 * j]; ss += (v[j].x * v[j].x + v[j].y * v[j].y) + (v[j].z * v[j].z + v[j].w * v[j].w); }
;     const float rinv = rsqrtf(wave_sum(ss, lane) * (1.f / DM) + 1e-6f);
; #pragma unroll
;     for (int j = 0; j < 8; ++j) { const f32x4 g = ((const f32x4*)gam)[lane + 64 * j]; v2u w; w.x = cvtpk(v[j].x * rinv * g.x, v[j].y * rinv * g.y); w.y = cvtpk(v[j].z * rinv * g.z, v[j].w * rinv * g.w); ((v2u*)orow)[lane + 64 * j] = w; }
; }
.Lrms_a_nopf:
	v_mul_f32_e32 v177, v64, v64
	v_mul_f32_e32 v178, v66, v66
	v_fmac_f32_e32 v177, v65, v65
	v_fmac_f32_e32 v178, v67, v67
	v_add_f32_e32 v176, v177, v178
	v_mul_f32_e32 v177, v68, v68
	v_mul_f32_e32 v178, v70, v70
	v_fmac_f32_e32 v177, v69, v69
	v_fmac_f32_e32 v178, v71, v71
	v_add_f32_e32 v177, v177, v178
	v_add_f32_e32 v176, v176, v177
	v_mul_f32_e32 v177, v72, v72
	v_mul_f32_e32 v178, v74, v74
	v_fmac_f32_e32 v177, v73, v73
	v_fmac_f32_e32 v178, v75, v75
	v_add_f32_e32 v177, v177, v178
	v_add_f32_e32 v176, v176, v177
	v_mul_f32_e32 v177, v76, v76
	v_mul_f32_e32 v178, v78, v78
	v_fmac_f32_e32 v177, v77, v77
	v_fmac_f32_e32 v178, v79, v79
	v_add_f32_e32 v177, v177, v178
	v_add_f32_e32 v176, v176, v177
	v_mul_f32_e32 v177, v80, v80
	v_mul_f32_e32 v178, v82, v82
	v_fmac_f32_e32 v177, v81, v81
	v_fmac_f32_e32 v178, v83, v83
	v_add_f32_e32 v177, v177, v178
	v_add_f32_e32 v176, v176, v177
	v_mul_f32_e32 v177, v84, v84
	v_mul_f32_e32 v178, v86, v86
	v_fmac_f32_e32 v177, v85, v85
	v_fmac_f32_e32 v178, v87, v87
	v_add_f32_e32 v177, v177, v178
	v_add_f32_e32 v176, v176, v177
	v_mul_f32_e32 v177, v88, v88
	v_mul_f32_e32 v178, v90, v90
	v_fmac_f32_e32 v177, v89, v89
	v_fmac_f32_e32 v178, v91, v91
	v_add_f32_e32 v177, v177, v178
	v_add_f32_e32 v176, v176, v177
	v_mul_f32_e32 v177, v92, v92
	v_mul_f32_e32 v178, v94, v94
	v_fmac_f32_e32 v177, v93, v93
	v_fmac_f32_e32 v178, v95, v95
	v_add_f32_e32 v177, v177, v178
	v_add_f32_e32 v176, v176, v177
	ds_bpermute_b32 v179, v52, v176
	s_waitcnt lgkmcnt(0)
	v_add_f32_e32 v176, v176, v179
	ds_bpermute_b32 v179, v53, v176
	s_waitcnt lgkmcnt(0)
	v_add_f32_e32 v176, v176, v179
	ds_bpermute_b32 v179, v54, v176
	s_waitcnt lgkmcnt(0)
	v_add_f32_e32 v176, v176, v179
	ds_bpermute_b32 v179, v55, v176
	s_waitcnt lgkmcnt(0)
	v_add_f32_e32 v176, v176, v179
	ds_bpermute_b32 v179, v56, v176
	s_waitcnt lgkmcnt(0)
	v_add_f32_e32 v176, v176, v179
	ds_bpermute_b32 v179, v57, v176
	s_waitcnt lgkmcnt(0)
	v_add_f32_e32 v176, v176, v179
	v_fmamk_f32 v176, v176, 0x3a000000, v230
	v_mul_f32_e32 v179, 0x4b800000, v176
	v_cmp_gt_f32_e32 vcc, s29, v176
	s_nop 1
	v_cndmask_b32_e32 v176, v176, v179, vcc
	v_rsq_f32_e32 v176, v176
	s_nop 0
	v_mul_f32_e32 v179, 0x45800000, v176
	v_cndmask_b32_e32 v180, v176, v179, vcc
	v_pk_mul_f32 v[64:65], v[64:65], v[180:181] op_sel_hi:[1,0]
	v_pk_mul_f32 v[66:67], v[66:67], v[180:181] op_sel_hi:[1,0]
	v_pk_mul_f32 v[64:65], v[128:129], v[64:65]
	v_pk_mul_f32 v[66:67], v[130:131], v[66:67]
	v_cvt_pk_bf16_f32 v182, v64, v65
	v_cvt_pk_bf16_f32 v183, v66, v67
	global_store_dwordx2 v[48:49], v[182:183], off
	v_pk_mul_f32 v[68:69], v[68:69], v[180:181] op_sel_hi:[1,0]
	v_pk_mul_f32 v[70:71], v[70:71], v[180:181] op_sel_hi:[1,0]
	v_pk_mul_f32 v[68:69], v[132:133], v[68:69]
	v_pk_mul_f32 v[70:71], v[134:135], v[70:71]
	v_cvt_pk_bf16_f32 v184, v68, v69
	v_cvt_pk_bf16_f32 v185, v70, v71
	global_store_dwordx2 v[48:49], v[184:185], off offset:512
	v_pk_mul_f32 v[72:73], v[72:73], v[180:181] op_sel_hi:[1,0]
	v_pk_mul_f32 v[74:75], v[74:75], v[180:181] op_sel_hi:[1,0]
	v_pk_mul_f32 v[72:73], v[136:137], v[72:73]
	v_pk_mul_f32 v[74:75], v[138:139], v[74:75]
	v_cvt_pk_bf16_f32 v182, v72, v73
	v_cvt_pk_bf16_f32 v183, v74, v75
	global_store_dwordx2 v[48:49], v[182:183], off offset:1024
	v_pk_mul_f32 v[76:77], v[76:77], v[180:181] op_sel_hi:[1,0]
	v_pk_mul_f32 v[78:79], v[78:79], v[180:181] op_sel_hi:[1,0]
	v_pk_mul_f32 v[76:77], v[140:141], v[76:77]
	v_pk_mul_f32 v[78:79], v[142:143], v[78:79]
	v_cvt_pk_bf16_f32 v184, v76, v77
	v_cvt_pk_bf16_f32 v185, v78, v79
	global_store_dwordx2 v[48:49], v[184:185], off offset:1536
	v_pk_mul_f32 v[80:81], v[80:81], v[180:181] op_sel_hi:[1,0]
	v_pk_mul_f32 v[82:83], v[82:83], v[180:181] op_sel_hi:[1,0]
	v_pk_mul_f32 v[80:81], v[144:145], v[80:81]
	v_pk_mul_f32 v[82:83], v[146:147], v[82:83]
	v_cvt_pk_bf16_f32 v182, v80, v81
	v_cvt_pk_bf16_f32 v183, v82, v83
	global_store_dwordx2 v[48:49], v[182:183], off offset:2048
	v_pk_mul_f32 v[84:85], v[84:85], v[180:181] op_sel_hi:[1,0]
	v_pk_mul_f32 v[86:87], v[86:87], v[180:181] op_sel_hi:[1,0]
	v_pk_mul_f32 v[84:85], v[148:149], v[84:85]
	v_pk_mul_f32 v[86:87], v[150:151], v[86:87]
	v_cvt_pk_bf16_f32 v184, v84, v85
	v_cvt_pk_bf16_f32 v185, v86, v87
	global_store_dwordx2 v[48:49], v[184:185], off offset:2560
	v_pk_mul_f32 v[88:89], v[88:89], v[180:181] op_sel_hi:[1,0]
	v_pk_mul_f32 v[90:91], v[90:91], v[180:181] op_sel_hi:[1,0]
	v_pk_mul_f32 v[88:89], v[152:153], v[88:89]
	v_pk_mul_f32 v[90:91], v[154:155], v[90:91]
	v_cvt_pk_bf16_f32 v182, v88, v89
	v_cvt_pk_bf16_f32 v183, v90, v91
	global_store_dwordx2 v[48:49], v[182:183], off offset:3072
	v_pk_mul_f32 v[92:93], v[92:93], v[180:181] op_sel_hi:[1,0]
	v_pk_mul_f32 v[94:95], v[94:95], v[180:181] op_sel_hi:[1,0]
	v_pk_mul_f32 v[92:93], v[156:157], v[92:93]
	v_pk_mul_f32 v[94:95], v[158:159], v[94:95]
	v_cvt_pk_bf16_f32 v184, v92, v93
	v_cvt_pk_bf16_f32 v185, v94, v95
	global_store_dwordx2 v[48:49], v[184:185], off offset:3584
	v_lshl_add_u64 v[48:49], v[48:49], 0, s[58:59]
	s_cmpk_gt_i32 s6, 0x3fff
	s_cbranch_scc0 .Lrms_a_loop

; __device__ __forceinline__ unsigned cvt_pk_bf16(float lo, float hi) { unsigned r; asm volatile("v_cvt_pk_bf16_f32 %0, %1, %2" : "=v"(r) : "v"(lo), "v"(hi)); return r; }
; __device__ __forceinline__ float bf_lo(unsigned w) { return __uint_as_float(w << 16); }
; __device__ __forceinline__ float bf_hi(unsigned w) { return __uint_as_float(w & 0xffff0000u); }
;     __device__ __forceinline__ void operator()(const f32x4 (&acc)[2][2][4][2], const Unit& u, int wr, int wc, int fr, int fq) const {
;     ...
;                 for (int bj = 0; bj < 2; ++bj) { const int row = row0 + ai * HALF + m * 16, col = col0 + bj * HALF;
;                     gv[m][bj] = *(const u32x4*)(G + (size_t)row * NGATE + br * 2048 + col);
;                     if (br > 0) { bf16_t* mp = Mg + (size_t)row * DM + col;
;                         q0[m][bj] = __hip_atomic_load((unsigned long long*)mp, __ATOMIC_RELAXED, __HIP_MEMORY_SCOPE_AGENT);
;                         q1[m][bj] = __hip_atomic_load((unsigned long long*)mp + 1, __ATOMIC_RELAXED, __HIP_MEMORY_SCOPE_AGENT); } }
; #pragma unroll
;             for (int m = 0; m < 4; ++m)
; #pragma unroll
;                 for (int bj = 0; bj < 2; ++bj) { const int row = row0 + ai * HALF + m * 16, col = col0 + bj * HALF; const u32x4 g4 = gv[m][bj];
;                     const f32x4 a0 = acc[ai][bj][m][0], a1 = acc[ai][bj][m][1];
;                     float f0 = a0[0] * bf_lo(g4.x), f1 = a0[1] * bf_hi(g4.x), f2 = a0[2] * bf_lo(g4.y), f3 = a0[3] * bf_hi(g4.y);
;                     float f4 = a1[0] * bf_lo(g4.z), f5 = a1[1] * bf_hi(g4.z), f6 = a1[2] * bf_lo(g4.w), f7 = a1[3] * bf_hi(g4.w);
;                     if (br > 0) {
;                         const unsigned p0 = (unsigned)q0[m][bj], p1 = (unsigned)(q0[m][bj] >> 32), p2 = (unsigned)q1[m][bj], p3 = (unsigned)(q1[m][bj] >> 32);
;                         f0 += bf_lo(p0); f1 += bf_hi(p0); f2 += bf_lo(p1); f3 += bf_hi(p1); f4 += bf_lo(p2); f5 += bf_hi(p2); f6 += bf_lo(p3); f7 += bf_hi(p3);
;                     }
;                     u32x4 w; w.x = cvt_pk_bf16(f0, f1); w.y = cvt_pk_bf16(f2, f3); w.z = cvt_pk_bf16(f4, f5); w.w = cvt_pk_bf16(f6, f7);
;                     *(u32x4*)(Mg + (size_t)row * DM + col) = w; }
.LBB0_89:
	s_lshl_b32 s8, s8, 8
	s_lshl_b32 s9, s42, 8
	s_and_b32 s8, s8, 0x700
	v_mov_b32_e32 v130, v171
	v_mov_b32_e32 v131, v239
	s_ashr_i32 s27, s42, 6
	s_and_b32 s9, s9, 0x3f00
	s_or_b32 s8, s8, s73
	s_add_i32 s9, s9, s67
	v_lshl_add_u32 v218, v131, 3, s8
	s_lshl_b32 s8, s27, 11
	v_add_u32_e32 v220, s9, v130
	s_ashr_i32 s9, s8, 31
	s_cmp_gt_i32 s27, 0
	s_cselect_b64 s[44:45], -1, 0
	s_lshl_b64 s[8:9], s[8:9], 1
	s_add_u32 s42, s63, s8
	s_addc_u32 s43, s66, s9
	v_mov_b64_e32 v[130:131], s[42:43]
	s_movk_i32 s8, 0x3000
	v_mad_i64_i32 v[130:131], s[8:9], v220, s8, v[130:131]
	v_ashrrev_i32_e32 v219, 31, v218
	v_lshl_add_u64 v[130:131], v[218:219], 1, v[130:131]
	v_ashrrev_i32_e32 v221, 31, v220
	v_lshlrev_b64 v[226:227], 12, v[220:221]
	v_lshl_add_u64 v[226:227], s[14:15], 0, v[226:227]
	v_lshl_add_u64 v[226:227], v[218:219], 1, v[226:227]
	v_mov_b32_e32 v222, v130
	v_mov_b32_e32 v223, v131
	v_mov_b32_e32 v228, 0x1000
	v_mov_b32_e32 v229, 0
	v_lshl_add_u64 v[224:225], v[222:223], 0, v[228:229]
	s_mov_b32 s8, 0x30000
	s_mov_b32 s9, 0
	s_mov_b32 s46, 0x10000
	s_mov_b32 s47, 0
	s_mov_b32 s44, 0xf0000
	s_mov_b32 s45, 0
	s_mov_b32 s42, 0x50000
	s_mov_b32 s43, 0
	s_cmp_eq_u32 s27, 2
	s_cbranch_scc1 .Lrb_final
	s_mov_b32 s44, 0x180000
	v_lshl_add_u64 v[226:227], v[222:223], 0, s[44:45]
	v_lshl_add_u64 v[228:229], v[224:225], 0, s[44:45]
	global_load_dwordx4 v[130:133], v[222:223], off
	global_load_dwordx4 v[186:189], v[224:225], off
	global_load_dwordx4 v[134:137], v[222:223], off offset:256
	global_load_dwordx4 v[190:193], v[224:225], off offset:256
	v_lshl_add_u64 v[222:223], v[222:223], 0, s[8:9]
	v_lshl_add_u64 v[224:225], v[224:225], 0, s[8:9]
	global_load_dwordx4 v[138:141], v[222:223], off
	global_load_dwordx4 v[194:197], v[224:225], off
	global_load_dwordx4 v[142:145], v[222:223], off offset:256
	global_load_dwordx4 v[198:201], v[224:225], off offset:256
	v_lshl_add_u64 v[222:223], v[222:223], 0, s[8:9]
	v_lshl_add_u64 v[224:225], v[224:225], 0, s[8:9]
	global_load_dwordx4 v[146:149], v[222:223], off
	global_load_dwordx4 v[202:205], v[224:225], off
	global_load_dwordx4 v[150:153], v[222:223], off offset:256
	global_load_dwordx4 v[206:209], v[224:225], off offset:256
	v_lshl_add_u64 v[222:223], v[222:223], 0, s[8:9]
	v_lshl_add_u64 v[224:225], v[224:225], 0, s[8:9]
	global_load_dwordx4 v[154:157], v[222:223], off
	global_load_dwordx4 v[210:213], v[224:225], off
	global_load_dwordx4 v[158:161], v[222:223], off offset:256
	global_load_dwordx4 v[214:217], v[224:225], off offset:256
	s_waitcnt vmcnt(12)
	v_lshlrev_b32_e32 v218, 16, v130
	v_and_b32_e32 v219, 0xffff0000, v130
	v_lshlrev_b32_e32 v220, 16, v186
	v_and_b32_e32 v221, 0xffff0000, v186
	v_max_f32_e32 v220, 0x21800000, v220
	v_max_f32_e32 v221, 0x21800000, v221
	v_max_f32_e32 v218, 0x21800000, v218
	v_max_f32_e32 v219, 0x21800000, v219
	v_rcp_f32_e32 v220, v220
	v_rcp_f32_e32 v221, v221
	v_mul_f32_e32 v218, v218, v220
	v_mul_f32_e32 v219, v219, v221
	v_pk_mul_f32 v[126:127], v[126:127], v[218:219]
	v_lshlrev_b32_e32 v242, 16, v131
	v_and_b32_e32 v243, 0xffff0000, v131
	v_lshlrev_b32_e32 v246, 16, v187
	v_and_b32_e32 v247, 0xffff0000, v187
	v_max_f32_e32 v246, 0x21800000, v246
	v_max_f32_e32 v247, 0x21800000, v247
	v_max_f32_e32 v242, 0x21800000, v242
	v_max_f32_e32 v243, 0x21800000, v243
	v_rcp_f32_e32 v246, v246
	v_rcp_f32_e32 v247, v247
	v_mul_f32_e32 v242, v242, v246
	v_mul_f32_e32 v243, v243, v247
	v_pk_mul_f32 v[128:129], v[128:129], v[242:243]
	v_lshlrev_b32_e32 v218, 16, v132
	v_and_b32_e32 v219, 0xffff0000, v132
	v_lshlrev_b32_e32 v220, 16, v188
	v_and_b32_e32 v221, 0xffff0000, v188
	v_max_f32_e32 v220, 0x21800000, v220
	v_max_f32_e32 v221, 0x21800000, v221
	v_max_f32_e32 v218, 0x21800000, v218
	v_max_f32_e32 v219, 0x21800000, v219
	v_rcp_f32_e32 v220, v220
	v_rcp_f32_e32 v221, v221
	v_mul_f32_e32 v218, v218, v220
	v_mul_f32_e32 v219, v219, v221
	v_pk_mul_f32 v[122:123], v[122:123], v[218:219]
	v_lshlrev_b32_e32 v242, 16, v133
	v_and_b32_e32 v243, 0xffff0000, v133
	v_lshlrev_b32_e32 v246, 16, v189
	v_and_b32_e32 v247, 0xffff0000, v189
	v_max_f32_e32 v246, 0x21800000, v246
	v_max_f32_e32 v247, 0x21800000, v247
	v_max_f32_e32 v242, 0x21800000, v242
	v_max_f32_e32 v243, 0x21800000, v243
	v_rcp_f32_e32 v246, v246
	v_rcp_f32_e32 v247, v247
	v_mul_f32_e32 v242, v242, v246
	v_mul_f32_e32 v243, v243, v247
	v_pk_mul_f32 v[124:125], v[124:125], v[242:243]
	v_lshlrev_b32_e32 v218, 16, v134
	v_and_b32_e32 v219, 0xffff0000, v134
	v_lshlrev_b32_e32 v220, 16, v190
	v_and_b32_e32 v221, 0xffff0000, v190
	v_max_f32_e32 v220, 0x21800000, v220
	v_max_f32_e32 v221, 0x21800000, v221
	v_max_f32_e32 v218, 0x21800000, v218
	v_max_f32_e32 v219, 0x21800000, v219
	v_rcp_f32_e32 v220, v220
	v_rcp_f32_e32 v221, v221
	v_mul_f32_e32 v218, v218, v220
	v_mul_f32_e32 v219, v219, v221
	v_pk_mul_f32 v[118:119], v[118:119], v[218:219]
	v_lshlrev_b32_e32 v242, 16, v135
	v_and_b32_e32 v243, 0xffff0000, v135
	v_lshlrev_b32_e32 v246, 16, v191
	v_and_b32_e32 v247, 0xffff0000, v191
	v_max_f32_e32 v246, 0x21800000, v246
	v_max_f32_e32 v247, 0x21800000, v247
	v_max_f32_e32 v242, 0x21800000, v242
	v_max_f32_e32 v243, 0x21800000, v243
	v_rcp_f32_e32 v246, v246
	v_rcp_f32_e32 v247, v247
	v_mul_f32_e32 v242, v242, v246
	v_mul_f32_e32 v243, v243, v247
	v_pk_mul_f32 v[120:121], v[120:121], v[242:243]
	v_lshlrev_b32_e32 v218, 16, v136
	v_and_b32_e32 v219, 0xffff0000, v136
	v_lshlrev_b32_e32 v220, 16, v192
	v_and_b32_e32 v221, 0xffff0000, v192
	v_max_f32_e32 v220, 0x21800000, v220
	v_max_f32_e32 v221, 0x21800000, v221
	v_max_f32_e32 v218, 0x21800000, v218
	v_max_f32_e32 v219, 0x21800000, v219
	v_rcp_f32_e32 v220, v220
	v_rcp_f32_e32 v221, v221
	v_mul_f32_e32 v218, v218, v220
	v_mul_f32_e32 v219, v219, v221
	v_pk_mul_f32 v[114:115], v[114:115], v[218:219]
	v_lshlrev_b32_e32 v242, 16, v137
	v_and_b32_e32 v243, 0xffff0000, v137
	v_lshlrev_b32_e32 v246, 16, v193
	v_and_b32_e32 v247, 0xffff0000, v193
	v_max_f32_e32 v246, 0x21800000, v246
	v_max_f32_e32 v247, 0x21800000, v247
	v_max_f32_e32 v242, 0x21800000, v242
	v_max_f32_e32 v243, 0x21800000, v243
	v_rcp_f32_e32 v246, v246
	v_rcp_f32_e32 v247, v247
	v_mul_f32_e32 v242, v242, v246
	v_mul_f32_e32 v243, v243, v247
	v_pk_mul_f32 v[116:117], v[116:117], v[242:243]
	global_load_dwordx4 v[130:133], v[226:227], off
	global_load_dwordx4 v[186:189], v[228:229], off
	global_load_dwordx4 v[134:137], v[226:227], off offset:256
	global_load_dwordx4 v[190:193], v[228:229], off offset:256
	s_waitcnt vmcnt(12)
; __device__ __forceinline__ unsigned cvt_pk_bf16(float lo, float hi) { unsigned r; asm volatile("v_cvt_pk_bf16_f32 %0, %1, %2" : "=v"(r) : "v"(lo), "v"(hi)); return r; }
; __device__ __forceinline__ float bf_lo(unsigned w) { return __uint_as_float(w << 16); }
; __device__ __forceinline__ float bf_hi(unsigned w) { return __uint_as_float(w & 0xffff0000u); }
;     __device__ __forceinline__ void operator()(const f32x4 (&acc)[2][2][4][2], const Unit& u, int wr, int wc, int fr, int fq) const {
;     ...
;                 for (int bj = 0; bj < 2; ++bj) { const int row = row0 + ai * HALF + m * 16, col = col0 + bj * HALF; const u32x4 g4 = gv[m][bj];
;                     const f32x4 a0 = acc[ai][bj][m][0], a1 = acc[ai][bj][m][1];
;                     float f0 = a0[0] * bf_lo(g4.x), f1 = a0[1] * bf_hi(g4.x), f2 = a0[2] * bf_lo(g4.y), f3 = a0[3] * bf_hi(g4.y);
;                     float f4 = a1[0] * bf_lo(g4.z), f5 = a1[1] * bf_hi(g4.z), f6 = a1[2] * bf_lo(g4.w), f7 = a1[3] * bf_hi(g4.w);
;                     if (br > 0) {
;                         const unsigned p0 = (unsigned)q0[m][bj], p1 = (unsigned)(q0[m][bj] >> 32), p2 = (unsigned)q1[m][bj], p3 = (unsigned)(q1[m][bj] >> 32);
;                         f0 += bf_lo(p0); f1 += bf_hi(p0); f2 += bf_lo(p1); f3 += bf_hi(p1); f4 += bf_lo(p2); f5 += bf_hi(p2); f6 += bf_lo(p3); f7 += bf_hi(p3);
;                     }
;                     u32x4 w; w.x = cvt_pk_bf16(f0, f1); w.y = cvt_pk_bf16(f2, f3); w.z = cvt_pk_bf16(f4, f5); w.w = cvt_pk_bf16(f6, f7);
;                     *(u32x4*)(Mg + (size_t)row * DM + col) = w; }
	v_lshlrev_b32_e32 v218, 16, v138
	v_and_b32_e32 v219, 0xffff0000, v138
	v_lshlrev_b32_e32 v220, 16, v194
	v_and_b32_e32 v221, 0xffff0000, v194
	v_max_f32_e32 v220, 0x21800000, v220
	v_max_f32_e32 v221, 0x21800000, v221
	v_max_f32_e32 v218, 0x21800000, v218
	v_max_f32_e32 v219, 0x21800000, v219
	v_rcp_f32_e32 v220, v220
	v_rcp_f32_e32 v221, v221
	v_mul_f32_e32 v218, v218, v220
	v_mul_f32_e32 v219, v219, v221
	v_pk_mul_f32 v[110:111], v[110:111], v[218:219]
	v_lshlrev_b32_e32 v242, 16, v139
	v_and_b32_e32 v243, 0xffff0000, v139
	v_lshlrev_b32_e32 v246, 16, v195
	v_and_b32_e32 v247, 0xffff0000, v195
	v_max_f32_e32 v246, 0x21800000, v246
	v_max_f32_e32 v247, 0x21800000, v247
	v_max_f32_e32 v242, 0x21800000, v242
	v_max_f32_e32 v243, 0x21800000, v243
	v_rcp_f32_e32 v246, v246
	v_rcp_f32_e32 v247, v247
	v_mul_f32_e32 v242, v242, v246
	v_mul_f32_e32 v243, v243, v247
	v_pk_mul_f32 v[112:113], v[112:113], v[242:243]
	v_lshlrev_b32_e32 v218, 16, v140
	v_and_b32_e32 v219, 0xffff0000, v140
	v_lshlrev_b32_e32 v220, 16, v196
	v_and_b32_e32 v221, 0xffff0000, v196
	v_max_f32_e32 v220, 0x21800000, v220
	v_max_f32_e32 v221, 0x21800000, v221
	v_max_f32_e32 v218, 0x21800000, v218
	v_max_f32_e32 v219, 0x21800000, v219
	v_rcp_f32_e32 v220, v220
	v_rcp_f32_e32 v221, v221
	v_mul_f32_e32 v218, v218, v220
	v_mul_f32_e32 v219, v219, v221
	v_pk_mul_f32 v[106:107], v[106:107], v[218:219]
	v_lshlrev_b32_e32 v242, 16, v141
	v_and_b32_e32 v243, 0xffff0000, v141
	v_lshlrev_b32_e32 v246, 16, v197
	v_and_b32_e32 v247, 0xffff0000, v197
	v_max_f32_e32 v246, 0x21800000, v246
	v_max_f32_e32 v247, 0x21800000, v247
	v_max_f32_e32 v242, 0x21800000, v242
	v_max_f32_e32 v243, 0x21800000, v243
	v_rcp_f32_e32 v246, v246
	v_rcp_f32_e32 v247, v247
	v_mul_f32_e32 v242, v242, v246
	v_mul_f32_e32 v243, v243, v247
	v_pk_mul_f32 v[108:109], v[108:109], v[242:243]
	v_lshlrev_b32_e32 v218, 16, v142
	v_and_b32_e32 v219, 0xffff0000, v142
	v_lshlrev_b32_e32 v220, 16, v198
	v_and_b32_e32 v221, 0xffff0000, v198
	v_max_f32_e32 v220, 0x21800000, v220
	v_max_f32_e32 v221, 0x21800000, v221
	v_max_f32_e32 v218, 0x21800000, v218
	v_max_f32_e32 v219, 0x21800000, v219
	v_rcp_f32_e32 v220, v220
	v_rcp_f32_e32 v221, v221
	v_mul_f32_e32 v218, v218, v220
	v_mul_f32_e32 v219, v219, v221
	v_pk_mul_f32 v[102:103], v[102:103], v[218:219]
	v_lshlrev_b32_e32 v242, 16, v143
	v_and_b32_e32 v243, 0xffff0000, v143
	v_lshlrev_b32_e32 v246, 16, v199
	v_and_b32_e32 v247, 0xffff0000, v199
	v_max_f32_e32 v246, 0x21800000, v246
	v_max_f32_e32 v247, 0x21800000, v247
	v_max_f32_e32 v242, 0x21800000, v242
	v_max_f32_e32 v243, 0x21800000, v243
	v_rcp_f32_e32 v246, v246
	v_rcp_f32_e32 v247, v247
	v_mul_f32_e32 v242, v242, v246
	v_mul_f32_e32 v243, v243, v247
	v_pk_mul_f32 v[104:105], v[104:105], v[242:243]
	v_lshlrev_b32_e32 v218, 16, v144
	v_and_b32_e32 v219, 0xffff0000, v144
	v_lshlrev_b32_e32 v220, 16, v200
	v_and_b32_e32 v221, 0xffff0000, v200
	v_max_f32_e32 v220, 0x21800000, v220
	v_max_f32_e32 v221, 0x21800000, v221
	v_max_f32_e32 v218, 0x21800000, v218
	v_max_f32_e32 v219, 0x21800000, v219
	v_rcp_f32_e32 v220, v220
	v_rcp_f32_e32 v221, v221
	v_mul_f32_e32 v218, v218, v220
	v_mul_f32_e32 v219, v219, v221
	v_pk_mul_f32 v[98:99], v[98:99], v[218:219]
	v_lshlrev_b32_e32 v242, 16, v145
	v_and_b32_e32 v243, 0xffff0000, v145
	v_lshlrev_b32_e32 v246, 16, v201
	v_and_b32_e32 v247, 0xffff0000, v201
	v_max_f32_e32 v246, 0x21800000, v246
	v_max_f32_e32 v247, 0x21800000, v247
	v_max_f32_e32 v242, 0x21800000, v242
	v_max_f32_e32 v243, 0x21800000, v243
	v_rcp_f32_e32 v246, v246
	v_rcp_f32_e32 v247, v247
	v_mul_f32_e32 v242, v242, v246
	v_mul_f32_e32 v243, v243, v247
	v_pk_mul_f32 v[100:101], v[100:101], v[242:243]
	v_lshl_add_u64 v[226:227], v[226:227], 0, s[8:9]
	v_lshl_add_u64 v[228:229], v[228:229], 0, s[8:9]
	global_load_dwordx4 v[138:141], v[226:227], off
	global_load_dwordx4 v[194:197], v[228:229], off
	global_load_dwordx4 v[142:145], v[226:227], off offset:256
	global_load_dwordx4 v[198:201], v[228:229], off offset:256
	s_waitcnt vmcnt(12)
	v_lshlrev_b32_e32 v218, 16, v146
	v_and_b32_e32 v219, 0xffff0000, v146
	v_lshlrev_b32_e32 v220, 16, v202
	v_and_b32_e32 v221, 0xffff0000, v202
	v_max_f32_e32 v220, 0x21800000, v220
	v_max_f32_e32 v221, 0x21800000, v221
	v_max_f32_e32 v218, 0x21800000, v218
	v_max_f32_e32 v219, 0x21800000, v219
	v_rcp_f32_e32 v220, v220
	v_rcp_f32_e32 v221, v221
	v_mul_f32_e32 v218, v218, v220
	v_mul_f32_e32 v219, v219, v221
	v_pk_mul_f32 v[94:95], v[94:95], v[218:219]
	v_lshlrev_b32_e32 v242, 16, v147
	v_and_b32_e32 v243, 0xffff0000, v147
	v_lshlrev_b32_e32 v246, 16, v203
	v_and_b32_e32 v247, 0xffff0000, v203
	v_max_f32_e32 v246, 0x21800000, v246
	v_max_f32_e32 v247, 0x21800000, v247
	v_max_f32_e32 v242, 0x21800000, v242
	v_max_f32_e32 v243, 0x21800000, v243
	v_rcp_f32_e32 v246, v246
	v_rcp_f32_e32 v247, v247
	v_mul_f32_e32 v242, v242, v246
	v_mul_f32_e32 v243, v243, v247
	v_pk_mul_f32 v[96:97], v[96:97], v[242:243]
	v_lshlrev_b32_e32 v218, 16, v148
	v_and_b32_e32 v219, 0xffff0000, v148
	v_lshlrev_b32_e32 v220, 16, v204
	v_and_b32_e32 v221, 0xffff0000, v204
	v_max_f32_e32 v220, 0x21800000, v220
	v_max_f32_e32 v221, 0x21800000, v221
	v_max_f32_e32 v218, 0x21800000, v218
	v_max_f32_e32 v219, 0x21800000, v219
	v_rcp_f32_e32 v220, v220
	v_rcp_f32_e32 v221, v221
	v_mul_f32_e32 v218, v218, v220
	v_mul_f32_e32 v219, v219, v221
	v_pk_mul_f32 v[90:91], v[90:91], v[218:219]
	v_lshlrev_b32_e32 v242, 16, v149
	v_and_b32_e32 v243, 0xffff0000, v149
	v_lshlrev_b32_e32 v246, 16, v205
	v_and_b32_e32 v247, 0xffff0000, v205
	v_max_f32_e32 v246, 0x21800000, v246
	v_max_f32_e32 v247, 0x21800000, v247
	v_max_f32_e32 v242, 0x21800000, v242
; __device__ __forceinline__ unsigned cvt_pk_bf16(float lo, float hi) { unsigned r; asm volatile("v_cvt_pk_bf16_f32 %0, %1, %2" : "=v"(r) : "v"(lo), "v"(hi)); return r; }
; __device__ __forceinline__ float bf_lo(unsigned w) { return __uint_as_float(w << 16); }
; __device__ __forceinline__ float bf_hi(unsigned w) { return __uint_as_float(w & 0xffff0000u); }
;     __device__ __forceinline__ void operator()(const f32x4 (&acc)[2][2][4][2], const Unit& u, int wr, int wc, int fr, int fq) const {
;     ...
;                 for (int bj = 0; bj < 2; ++bj) { const int row = row0 + ai * HALF + m * 16, col = col0 + bj * HALF; const u32x4 g4 = gv[m][bj];
;                     const f32x4 a0 = acc[ai][bj][m][0], a1 = acc[ai][bj][m][1];
;                     float f0 = a0[0] * bf_lo(g4.x), f1 = a0[1] * bf_hi(g4.x), f2 = a0[2] * bf_lo(g4.y), f3 = a0[3] * bf_hi(g4.y);
;                     float f4 = a1[0] * bf_lo(g4.z), f5 = a1[1] * bf_hi(g4.z), f6 = a1[2] * bf_lo(g4.w), f7 = a1[3] * bf_hi(g4.w);
;                     if (br > 0) {
;                         const unsigned p0 = (unsigned)q0[m][bj], p1 = (unsigned)(q0[m][bj] >> 32), p2 = (unsigned)q1[m][bj], p3 = (unsigned)(q1[m][bj] >> 32);
;                         f0 += bf_lo(p0); f1 += bf_hi(p0); f2 += bf_lo(p1); f3 += bf_hi(p1); f4 += bf_lo(p2); f5 += bf_hi(p2); f6 += bf_lo(p3); f7 += bf_hi(p3);
;                     }
;                     u32x4 w; w.x = cvt_pk_bf16(f0, f1); w.y = cvt_pk_bf16(f2, f3); w.z = cvt_pk_bf16(f4, f5); w.w = cvt_pk_bf16(f6, f7);
;                     *(u32x4*)(Mg + (size_t)row * DM + col) = w; }
	v_max_f32_e32 v243, 0x21800000, v243
	v_rcp_f32_e32 v246, v246
	v_rcp_f32_e32 v247, v247
	v_mul_f32_e32 v242, v242, v246
	v_mul_f32_e32 v243, v243, v247
	v_pk_mul_f32 v[92:93], v[92:93], v[242:243]
	v_lshlrev_b32_e32 v218, 16, v150
	v_and_b32_e32 v219, 0xffff0000, v150
	v_lshlrev_b32_e32 v220, 16, v206
	v_and_b32_e32 v221, 0xffff0000, v206
	v_max_f32_e32 v220, 0x21800000, v220
	v_max_f32_e32 v221, 0x21800000, v221
	v_max_f32_e32 v218, 0x21800000, v218
	v_max_f32_e32 v219, 0x21800000, v219
	v_rcp_f32_e32 v220, v220
	v_rcp_f32_e32 v221, v221
	v_mul_f32_e32 v218, v218, v220
	v_mul_f32_e32 v219, v219, v221
	v_pk_mul_f32 v[86:87], v[86:87], v[218:219]
	v_lshlrev_b32_e32 v242, 16, v151
	v_and_b32_e32 v243, 0xffff0000, v151
	v_lshlrev_b32_e32 v246, 16, v207
	v_and_b32_e32 v247, 0xffff0000, v207
	v_max_f32_e32 v246, 0x21800000, v246
	v_max_f32_e32 v247, 0x21800000, v247
	v_max_f32_e32 v242, 0x21800000, v242
	v_max_f32_e32 v243, 0x21800000, v243
	v_rcp_f32_e32 v246, v246
	v_rcp_f32_e32 v247, v247
	v_mul_f32_e32 v242, v242, v246
	v_mul_f32_e32 v243, v243, v247
	v_pk_mul_f32 v[88:89], v[88:89], v[242:243]
	v_lshlrev_b32_e32 v218, 16, v152
	v_and_b32_e32 v219, 0xffff0000, v152
	v_lshlrev_b32_e32 v220, 16, v208
	v_and_b32_e32 v221, 0xffff0000, v208
	v_max_f32_e32 v220, 0x21800000, v220
	v_max_f32_e32 v221, 0x21800000, v221
	v_max_f32_e32 v218, 0x21800000, v218
	v_max_f32_e32 v219, 0x21800000, v219
	v_rcp_f32_e32 v220, v220
	v_rcp_f32_e32 v221, v221
	v_mul_f32_e32 v218, v218, v220
	v_mul_f32_e32 v219, v219, v221
	v_pk_mul_f32 v[82:83], v[82:83], v[218:219]
	v_lshlrev_b32_e32 v242, 16, v153
	v_and_b32_e32 v243, 0xffff0000, v153
	v_lshlrev_b32_e32 v246, 16, v209
	v_and_b32_e32 v247, 0xffff0000, v209
	v_max_f32_e32 v246, 0x21800000, v246
	v_max_f32_e32 v247, 0x21800000, v247
	v_max_f32_e32 v242, 0x21800000, v242
	v_max_f32_e32 v243, 0x21800000, v243
	v_rcp_f32_e32 v246, v246
	v_rcp_f32_e32 v247, v247
	v_mul_f32_e32 v242, v242, v246
	v_mul_f32_e32 v243, v243, v247
	v_pk_mul_f32 v[84:85], v[84:85], v[242:243]
	v_lshl_add_u64 v[226:227], v[226:227], 0, s[8:9]
	v_lshl_add_u64 v[228:229], v[228:229], 0, s[8:9]
	global_load_dwordx4 v[146:149], v[226:227], off
	global_load_dwordx4 v[202:205], v[228:229], off
	global_load_dwordx4 v[150:153], v[226:227], off offset:256
	global_load_dwordx4 v[206:209], v[228:229], off offset:256
	s_waitcnt vmcnt(12)
	v_lshlrev_b32_e32 v218, 16, v154
	v_and_b32_e32 v219, 0xffff0000, v154
	v_lshlrev_b32_e32 v220, 16, v210
	v_and_b32_e32 v221, 0xffff0000, v210
	v_max_f32_e32 v220, 0x21800000, v220
	v_max_f32_e32 v221, 0x21800000, v221
	v_max_f32_e32 v218, 0x21800000, v218
	v_max_f32_e32 v219, 0x21800000, v219
	v_rcp_f32_e32 v220, v220
	v_rcp_f32_e32 v221, v221
	v_mul_f32_e32 v218, v218, v220
	v_mul_f32_e32 v219, v219, v221
	v_pk_mul_f32 v[78:79], v[78:79], v[218:219]
	v_lshlrev_b32_e32 v242, 16, v155
	v_and_b32_e32 v243, 0xffff0000, v155
	v_lshlrev_b32_e32 v246, 16, v211
	v_and_b32_e32 v247, 0xffff0000, v211
	v_max_f32_e32 v246, 0x21800000, v246
	v_max_f32_e32 v247, 0x21800000, v247
	v_max_f32_e32 v242, 0x21800000, v242
	v_max_f32_e32 v243, 0x21800000, v243
	v_rcp_f32_e32 v246, v246
	v_rcp_f32_e32 v247, v247
	v_mul_f32_e32 v242, v242, v246
	v_mul_f32_e32 v243, v243, v247
	v_pk_mul_f32 v[80:81], v[80:81], v[242:243]
	v_lshlrev_b32_e32 v218, 16, v156
	v_and_b32_e32 v219, 0xffff0000, v156
	v_lshlrev_b32_e32 v220, 16, v212
	v_and_b32_e32 v221, 0xffff0000, v212
	v_max_f32_e32 v220, 0x21800000, v220
	v_max_f32_e32 v221, 0x21800000, v221
	v_max_f32_e32 v218, 0x21800000, v218
	v_max_f32_e32 v219, 0x21800000, v219
	v_rcp_f32_e32 v220, v220
	v_rcp_f32_e32 v221, v221
	v_mul_f32_e32 v218, v218, v220
	v_mul_f32_e32 v219, v219, v221
	v_pk_mul_f32 v[74:75], v[74:75], v[218:219]
	v_lshlrev_b32_e32 v242, 16, v157
	v_and_b32_e32 v243, 0xffff0000, v157
	v_lshlrev_b32_e32 v246, 16, v213
	v_and_b32_e32 v247, 0xffff0000, v213
	v_max_f32_e32 v246, 0x21800000, v246
	v_max_f32_e32 v247, 0x21800000, v247
	v_max_f32_e32 v242, 0x21800000, v242
	v_max_f32_e32 v243, 0x21800000, v243
	v_rcp_f32_e32 v246, v246
	v_rcp_f32_e32 v247, v247
	v_mul_f32_e32 v242, v242, v246
	v_mul_f32_e32 v243, v243, v247
	v_pk_mul_f32 v[76:77], v[76:77], v[242:243]
	v_lshlrev_b32_e32 v218, 16, v158
	v_and_b32_e32 v219, 0xffff0000, v158
	v_lshlrev_b32_e32 v220, 16, v214
	v_and_b32_e32 v221, 0xffff0000, v214
	v_max_f32_e32 v220, 0x21800000, v220
	v_max_f32_e32 v221, 0x21800000, v221
	v_max_f32_e32 v218, 0x21800000, v218
	v_max_f32_e32 v219, 0x21800000, v219
	v_rcp_f32_e32 v220, v220
	v_rcp_f32_e32 v221, v221
	v_mul_f32_e32 v218, v218, v220
	v_mul_f32_e32 v219, v219, v221
	v_pk_mul_f32 v[70:71], v[70:71], v[218:219]
	v_lshlrev_b32_e32 v242, 16, v159
	v_and_b32_e32 v243, 0xffff0000, v159
	v_lshlrev_b32_e32 v246, 16, v215
	v_and_b32_e32 v247, 0xffff0000, v215
	v_max_f32_e32 v246, 0x21800000, v246
	v_max_f32_e32 v247, 0x21800000, v247
	v_max_f32_e32 v242, 0x21800000, v242
	v_max_f32_e32 v243, 0x21800000, v243
	v_rcp_f32_e32 v246, v246
	v_rcp_f32_e32 v247, v247
	v_mul_f32_e32 v242, v242, v246
	v_mul_f32_e32 v243, v243, v247
	v_pk_mul_f32 v[72:73], v[72:73], v[242:243]
	v_lshlrev_b32_e32 v218, 16, v160
	v_and_b32_e32 v219, 0xffff0000, v160
	v_lshlrev_b32_e32 v220, 16, v216
	v_and_b32_e32 v221, 0xffff0000, v216
	v_max_f32_e32 v220, 0x21800000, v220
	v_max_f32_e32 v221, 0x21800000, v221
	v_max_f32_e32 v218, 0x21800000, v218
	v_max_f32_e32 v219, 0x21800000, v219
	v_rcp_f32_e32 v220, v220
	v_rcp_f32_e32 v221, v221
	v_mul_f32_e32 v218, v218, v220
	v_mul_f32_e32 v219, v219, v221
	v_pk_mul_f32 v[66:67], v[66:67], v[218:219]
	v_lshlrev_b32_e32 v242, 16, v161
	v_and_b32_e32 v243, 0xffff0000, v161
	v_lshlrev_b32_e32 v246, 16, v217
	v_and_b32_e32 v247, 0xffff0000, v217
	v_max_f32_e32 v246, 0x21800000, v246
	v_max_f32_e32 v247, 0x21800000, v247
	v_max_f32_e32 v242, 0x21800000, v242
	v_max_f32_e32 v243, 0x21800000, v243
	v_rcp_f32_e32 v246, v246
	v_rcp_f32_e32 v247, v247
	v_mul_f32_e32 v242, v242, v246
	v_mul_f32_e32 v243, v243, v247
	v_pk_mul_f32 v[68:69], v[68:69], v[242:243]
	v_lshl_add_u64 v[226:227], v[226:227], 0, s[8:9]
	v_lshl_add_u64 v[228:229], v[228:229], 0, s[8:9]
	global_load_dwordx4 v[154:157], v[226:227], off
	global_load_dwordx4 v[210:213], v[228:229], off
	global_load_dwordx4 v[158:161], v[226:227], off offset:256
	global_load_dwordx4 v[214:217], v[228:229], off offset:256
	s_waitcnt vmcnt(12)
; __device__ __forceinline__ unsigned cvt_pk_bf16(float lo, float hi) { unsigned r; asm volatile("v_cvt_pk_bf16_f32 %0, %1, %2" : "=v"(r) : "v"(lo), "v"(hi)); return r; }
; __device__ __forceinline__ float bf_lo(unsigned w) { return __uint_as_float(w << 16); }
; __device__ __forceinline__ float bf_hi(unsigned w) { return __uint_as_float(w & 0xffff0000u); }
;     __device__ __forceinline__ void operator()(const f32x4 (&acc)[2][2][4][2], const Unit& u, int wr, int wc, int fr, int fq) const {
;     ...
;                 for (int bj = 0; bj < 2; ++bj) { const int row = row0 + ai * HALF + m * 16, col = col0 + bj * HALF; const u32x4 g4 = gv[m][bj];
;                     const f32x4 a0 = acc[ai][bj][m][0], a1 = acc[ai][bj][m][1];
;                     float f0 = a0[0] * bf_lo(g4.x), f1 = a0[1] * bf_hi(g4.x), f2 = a0[2] * bf_lo(g4.y), f3 = a0[3] * bf_hi(g4.y);
;                     float f4 = a1[0] * bf_lo(g4.z), f5 = a1[1] * bf_hi(g4.z), f6 = a1[2] * bf_lo(g4.w), f7 = a1[3] * bf_hi(g4.w);
;                     if (br > 0) {
;                         const unsigned p0 = (unsigned)q0[m][bj], p1 = (unsigned)(q0[m][bj] >> 32), p2 = (unsigned)q1[m][bj], p3 = (unsigned)(q1[m][bj] >> 32);
;                         f0 += bf_lo(p0); f1 += bf_hi(p0); f2 += bf_lo(p1); f3 += bf_hi(p1); f4 += bf_lo(p2); f5 += bf_hi(p2); f6 += bf_lo(p3); f7 += bf_hi(p3);
;                     }
;                     u32x4 w; w.x = cvt_pk_bf16(f0, f1); w.y = cvt_pk_bf16(f2, f3); w.z = cvt_pk_bf16(f4, f5); w.w = cvt_pk_bf16(f6, f7);
;                     *(u32x4*)(Mg + (size_t)row * DM + col) = w; }
	v_lshlrev_b32_e32 v218, 16, v130
	v_and_b32_e32 v219, 0xffff0000, v130
	v_lshlrev_b32_e32 v220, 16, v186
	v_and_b32_e32 v221, 0xffff0000, v186
	v_max_f32_e32 v220, 0x21800000, v220
	v_max_f32_e32 v221, 0x21800000, v221
	v_max_f32_e32 v218, 0x21800000, v218
	v_max_f32_e32 v219, 0x21800000, v219
	v_rcp_f32_e32 v220, v220
	v_rcp_f32_e32 v221, v221
	v_mul_f32_e32 v218, v218, v220
	v_mul_f32_e32 v219, v219, v221
	v_pk_mul_f32 v[62:63], v[62:63], v[218:219]
	v_lshlrev_b32_e32 v242, 16, v131
	v_and_b32_e32 v243, 0xffff0000, v131
	v_lshlrev_b32_e32 v246, 16, v187
	v_and_b32_e32 v247, 0xffff0000, v187
	v_max_f32_e32 v246, 0x21800000, v246
	v_max_f32_e32 v247, 0x21800000, v247
	v_max_f32_e32 v242, 0x21800000, v242
	v_max_f32_e32 v243, 0x21800000, v243
	v_rcp_f32_e32 v246, v246
	v_rcp_f32_e32 v247, v247
	v_mul_f32_e32 v242, v242, v246
	v_mul_f32_e32 v243, v243, v247
	v_pk_mul_f32 v[64:65], v[64:65], v[242:243]
	v_lshlrev_b32_e32 v218, 16, v132
	v_and_b32_e32 v219, 0xffff0000, v132
	v_lshlrev_b32_e32 v220, 16, v188
	v_and_b32_e32 v221, 0xffff0000, v188
	v_max_f32_e32 v220, 0x21800000, v220
	v_max_f32_e32 v221, 0x21800000, v221
	v_max_f32_e32 v218, 0x21800000, v218
	v_max_f32_e32 v219, 0x21800000, v219
	v_rcp_f32_e32 v220, v220
	v_rcp_f32_e32 v221, v221
	v_mul_f32_e32 v218, v218, v220
	v_mul_f32_e32 v219, v219, v221
	v_pk_mul_f32 v[58:59], v[58:59], v[218:219]
	v_lshlrev_b32_e32 v242, 16, v133
	v_and_b32_e32 v243, 0xffff0000, v133
	v_lshlrev_b32_e32 v246, 16, v189
	v_and_b32_e32 v247, 0xffff0000, v189
	v_max_f32_e32 v246, 0x21800000, v246
	v_max_f32_e32 v247, 0x21800000, v247
	v_max_f32_e32 v242, 0x21800000, v242
	v_max_f32_e32 v243, 0x21800000, v243
	v_rcp_f32_e32 v246, v246
	v_rcp_f32_e32 v247, v247
	v_mul_f32_e32 v242, v242, v246
	v_mul_f32_e32 v243, v243, v247
	v_pk_mul_f32 v[60:61], v[60:61], v[242:243]
	v_lshlrev_b32_e32 v218, 16, v134
	v_and_b32_e32 v219, 0xffff0000, v134
	v_lshlrev_b32_e32 v220, 16, v190
	v_and_b32_e32 v221, 0xffff0000, v190
	v_max_f32_e32 v220, 0x21800000, v220
	v_max_f32_e32 v221, 0x21800000, v221
	v_max_f32_e32 v218, 0x21800000, v218
	v_max_f32_e32 v219, 0x21800000, v219
	v_rcp_f32_e32 v220, v220
	v_rcp_f32_e32 v221, v221
	v_mul_f32_e32 v218, v218, v220
	v_mul_f32_e32 v219, v219, v221
	v_pk_mul_f32 v[54:55], v[54:55], v[218:219]
	v_lshlrev_b32_e32 v242, 16, v135
	v_and_b32_e32 v243, 0xffff0000, v135
	v_lshlrev_b32_e32 v246, 16, v191
	v_and_b32_e32 v247, 0xffff0000, v191
	v_max_f32_e32 v246, 0x21800000, v246
	v_max_f32_e32 v247, 0x21800000, v247
	v_max_f32_e32 v242, 0x21800000, v242
	v_max_f32_e32 v243, 0x21800000, v243
	v_rcp_f32_e32 v246, v246
	v_rcp_f32_e32 v247, v247
	v_mul_f32_e32 v242, v242, v246
	v_mul_f32_e32 v243, v243, v247
	v_pk_mul_f32 v[56:57], v[56:57], v[242:243]
	v_lshlrev_b32_e32 v218, 16, v136
	v_and_b32_e32 v219, 0xffff0000, v136
	v_lshlrev_b32_e32 v220, 16, v192
	v_and_b32_e32 v221, 0xffff0000, v192
	v_max_f32_e32 v220, 0x21800000, v220
	v_max_f32_e32 v221, 0x21800000, v221
	v_max_f32_e32 v218, 0x21800000, v218
	v_max_f32_e32 v219, 0x21800000, v219
	v_rcp_f32_e32 v220, v220
	v_rcp_f32_e32 v221, v221
	v_mul_f32_e32 v218, v218, v220
	v_mul_f32_e32 v219, v219, v221
	v_pk_mul_f32 v[50:51], v[50:51], v[218:219]
	v_lshlrev_b32_e32 v242, 16, v137
	v_and_b32_e32 v243, 0xffff0000, v137
	v_lshlrev_b32_e32 v246, 16, v193
	v_and_b32_e32 v247, 0xffff0000, v193
	v_max_f32_e32 v246, 0x21800000, v246
	v_max_f32_e32 v247, 0x21800000, v247
	v_max_f32_e32 v242, 0x21800000, v242
	v_max_f32_e32 v243, 0x21800000, v243
	v_rcp_f32_e32 v246, v246
	v_rcp_f32_e32 v247, v247
	v_mul_f32_e32 v242, v242, v246
	v_mul_f32_e32 v243, v243, v247
	v_pk_mul_f32 v[52:53], v[52:53], v[242:243]
	s_waitcnt vmcnt(8)
	v_lshlrev_b32_e32 v218, 16, v138
	v_and_b32_e32 v219, 0xffff0000, v138
	v_lshlrev_b32_e32 v220, 16, v194
	v_and_b32_e32 v221, 0xffff0000, v194
	v_max_f32_e32 v220, 0x21800000, v220
	v_max_f32_e32 v221, 0x21800000, v221
	v_max_f32_e32 v218, 0x21800000, v218
	v_max_f32_e32 v219, 0x21800000, v219
	v_rcp_f32_e32 v220, v220
	v_rcp_f32_e32 v221, v221
	v_mul_f32_e32 v218, v218, v220
	v_mul_f32_e32 v219, v219, v221
	v_pk_mul_f32 v[46:47], v[46:47], v[218:219]
	v_lshlrev_b32_e32 v242, 16, v139
	v_and_b32_e32 v243, 0xffff0000, v139
	v_lshlrev_b32_e32 v246, 16, v195
	v_and_b32_e32 v247, 0xffff0000, v195
	v_max_f32_e32 v246, 0x21800000, v246
	v_max_f32_e32 v247, 0x21800000, v247
	v_max_f32_e32 v242, 0x21800000, v242
	v_max_f32_e32 v243, 0x21800000, v243
	v_rcp_f32_e32 v246, v246
	v_rcp_f32_e32 v247, v247
	v_mul_f32_e32 v242, v242, v246
	v_mul_f32_e32 v243, v243, v247
	v_pk_mul_f32 v[48:49], v[48:49], v[242:243]
	v_lshlrev_b32_e32 v218, 16, v140
	v_and_b32_e32 v219, 0xffff0000, v140
	v_lshlrev_b32_e32 v220, 16, v196
	v_and_b32_e32 v221, 0xffff0000, v196
	v_max_f32_e32 v220, 0x21800000, v220
	v_max_f32_e32 v221, 0x21800000, v221
	v_max_f32_e32 v218, 0x21800000, v218
	v_max_f32_e32 v219, 0x21800000, v219
	v_rcp_f32_e32 v220, v220
	v_rcp_f32_e32 v221, v221
	v_mul_f32_e32 v218, v218, v220
	v_mul_f32_e32 v219, v219, v221
	v_pk_mul_f32 v[42:43], v[42:43], v[218:219]
	v_lshlrev_b32_e32 v242, 16, v141
	v_and_b32_e32 v243, 0xffff0000, v141
	v_lshlrev_b32_e32 v246, 16, v197
	v_and_b32_e32 v247, 0xffff0000, v197
	v_max_f32_e32 v246, 0x21800000, v246
	v_max_f32_e32 v247, 0x21800000, v247
	v_max_f32_e32 v242, 0x21800000, v242
	v_max_f32_e32 v243, 0x21800000, v243
	v_rcp_f32_e32 v246, v246
	v_rcp_f32_e32 v247, v247
	v_mul_f32_e32 v242, v242, v246
	v_mul_f32_e32 v243, v243, v247
	v_pk_mul_f32 v[44:45], v[44:45], v[242:243]
	v_lshlrev_b32_e32 v218, 16, v142
	v_and_b32_e32 v219, 0xffff0000, v142
	v_lshlrev_b32_e32 v220, 16, v198
	v_and_b32_e32 v221, 0xffff0000, v198
; __device__ __forceinline__ unsigned cvt_pk_bf16(float lo, float hi) { unsigned r; asm volatile("v_cvt_pk_bf16_f32 %0, %1, %2" : "=v"(r) : "v"(lo), "v"(hi)); return r; }
; __device__ __forceinline__ float bf_lo(unsigned w) { return __uint_as_float(w << 16); }
; __device__ __forceinline__ float bf_hi(unsigned w) { return __uint_as_float(w & 0xffff0000u); }
;     __device__ __forceinline__ void operator()(const f32x4 (&acc)[2][2][4][2], const Unit& u, int wr, int wc, int fr, int fq) const {
;     ...
;                 for (int bj = 0; bj < 2; ++bj) { const int row = row0 + ai * HALF + m * 16, col = col0 + bj * HALF; const u32x4 g4 = gv[m][bj];
;                     const f32x4 a0 = acc[ai][bj][m][0], a1 = acc[ai][bj][m][1];
;                     float f0 = a0[0] * bf_lo(g4.x), f1 = a0[1] * bf_hi(g4.x), f2 = a0[2] * bf_lo(g4.y), f3 = a0[3] * bf_hi(g4.y);
;                     float f4 = a1[0] * bf_lo(g4.z), f5 = a1[1] * bf_hi(g4.z), f6 = a1[2] * bf_lo(g4.w), f7 = a1[3] * bf_hi(g4.w);
;                     if (br > 0) {
;                         const unsigned p0 = (unsigned)q0[m][bj], p1 = (unsigned)(q0[m][bj] >> 32), p2 = (unsigned)q1[m][bj], p3 = (unsigned)(q1[m][bj] >> 32);
;                         f0 += bf_lo(p0); f1 += bf_hi(p0); f2 += bf_lo(p1); f3 += bf_hi(p1); f4 += bf_lo(p2); f5 += bf_hi(p2); f6 += bf_lo(p3); f7 += bf_hi(p3);
;                     }
;                     u32x4 w; w.x = cvt_pk_bf16(f0, f1); w.y = cvt_pk_bf16(f2, f3); w.z = cvt_pk_bf16(f4, f5); w.w = cvt_pk_bf16(f6, f7);
;                     *(u32x4*)(Mg + (size_t)row * DM + col) = w; }
	v_max_f32_e32 v220, 0x21800000, v220
	v_max_f32_e32 v221, 0x21800000, v221
	v_max_f32_e32 v218, 0x21800000, v218
	v_max_f32_e32 v219, 0x21800000, v219
	v_rcp_f32_e32 v220, v220
	v_rcp_f32_e32 v221, v221
	v_mul_f32_e32 v218, v218, v220
	v_mul_f32_e32 v219, v219, v221
	v_pk_mul_f32 v[38:39], v[38:39], v[218:219]
	v_lshlrev_b32_e32 v242, 16, v143
	v_and_b32_e32 v243, 0xffff0000, v143
	v_lshlrev_b32_e32 v246, 16, v199
	v_and_b32_e32 v247, 0xffff0000, v199
	v_max_f32_e32 v246, 0x21800000, v246
	v_max_f32_e32 v247, 0x21800000, v247
	v_max_f32_e32 v242, 0x21800000, v242
	v_max_f32_e32 v243, 0x21800000, v243
	v_rcp_f32_e32 v246, v246
	v_rcp_f32_e32 v247, v247
	v_mul_f32_e32 v242, v242, v246
	v_mul_f32_e32 v243, v243, v247
	v_pk_mul_f32 v[40:41], v[40:41], v[242:243]
	v_lshlrev_b32_e32 v218, 16, v144
	v_and_b32_e32 v219, 0xffff0000, v144
	v_lshlrev_b32_e32 v220, 16, v200
	v_and_b32_e32 v221, 0xffff0000, v200
	v_max_f32_e32 v220, 0x21800000, v220
	v_max_f32_e32 v221, 0x21800000, v221
	v_max_f32_e32 v218, 0x21800000, v218
	v_max_f32_e32 v219, 0x21800000, v219
	v_rcp_f32_e32 v220, v220
	v_rcp_f32_e32 v221, v221
	v_mul_f32_e32 v218, v218, v220
	v_mul_f32_e32 v219, v219, v221
	v_pk_mul_f32 v[34:35], v[34:35], v[218:219]
	v_lshlrev_b32_e32 v242, 16, v145
	v_and_b32_e32 v243, 0xffff0000, v145
	v_lshlrev_b32_e32 v246, 16, v201
	v_and_b32_e32 v247, 0xffff0000, v201
	v_max_f32_e32 v246, 0x21800000, v246
	v_max_f32_e32 v247, 0x21800000, v247
	v_max_f32_e32 v242, 0x21800000, v242
	v_max_f32_e32 v243, 0x21800000, v243
	v_rcp_f32_e32 v246, v246
	v_rcp_f32_e32 v247, v247
	v_mul_f32_e32 v242, v242, v246
	v_mul_f32_e32 v243, v243, v247
	v_pk_mul_f32 v[36:37], v[36:37], v[242:243]
	s_waitcnt vmcnt(4)
	v_lshlrev_b32_e32 v218, 16, v146
	v_and_b32_e32 v219, 0xffff0000, v146
	v_lshlrev_b32_e32 v220, 16, v202
	v_and_b32_e32 v221, 0xffff0000, v202
	v_max_f32_e32 v220, 0x21800000, v220
	v_max_f32_e32 v221, 0x21800000, v221
	v_max_f32_e32 v218, 0x21800000, v218
	v_max_f32_e32 v219, 0x21800000, v219
	v_rcp_f32_e32 v220, v220
	v_rcp_f32_e32 v221, v221
	v_mul_f32_e32 v218, v218, v220
	v_mul_f32_e32 v219, v219, v221
	v_pk_mul_f32 v[30:31], v[30:31], v[218:219]
	v_lshlrev_b32_e32 v242, 16, v147
	v_and_b32_e32 v243, 0xffff0000, v147
	v_lshlrev_b32_e32 v246, 16, v203
	v_and_b32_e32 v247, 0xffff0000, v203
	v_max_f32_e32 v246, 0x21800000, v246
	v_max_f32_e32 v247, 0x21800000, v247
	v_max_f32_e32 v242, 0x21800000, v242
	v_max_f32_e32 v243, 0x21800000, v243
	v_rcp_f32_e32 v246, v246
	v_rcp_f32_e32 v247, v247
	v_mul_f32_e32 v242, v242, v246
	v_mul_f32_e32 v243, v243, v247
	v_pk_mul_f32 v[32:33], v[32:33], v[242:243]
	v_lshlrev_b32_e32 v218, 16, v148
	v_and_b32_e32 v219, 0xffff0000, v148
	v_lshlrev_b32_e32 v220, 16, v204
	v_and_b32_e32 v221, 0xffff0000, v204
	v_max_f32_e32 v220, 0x21800000, v220
	v_max_f32_e32 v221, 0x21800000, v221
	v_max_f32_e32 v218, 0x21800000, v218
	v_max_f32_e32 v219, 0x21800000, v219
	v_rcp_f32_e32 v220, v220
	v_rcp_f32_e32 v221, v221
	v_mul_f32_e32 v218, v218, v220
	v_mul_f32_e32 v219, v219, v221
	v_pk_mul_f32 v[26:27], v[26:27], v[218:219]
	v_lshlrev_b32_e32 v242, 16, v149
	v_and_b32_e32 v243, 0xffff0000, v149
	v_lshlrev_b32_e32 v246, 16, v205
	v_and_b32_e32 v247, 0xffff0000, v205
	v_max_f32_e32 v246, 0x21800000, v246
	v_max_f32_e32 v247, 0x21800000, v247
	v_max_f32_e32 v242, 0x21800000, v242
	v_max_f32_e32 v243, 0x21800000, v243
	v_rcp_f32_e32 v246, v246
	v_rcp_f32_e32 v247, v247
	v_mul_f32_e32 v242, v242, v246
	v_mul_f32_e32 v243, v243, v247
	v_pk_mul_f32 v[28:29], v[28:29], v[242:243]
	v_lshlrev_b32_e32 v218, 16, v150
	v_and_b32_e32 v219, 0xffff0000, v150
	v_lshlrev_b32_e32 v220, 16, v206
	v_and_b32_e32 v221, 0xffff0000, v206
	v_max_f32_e32 v220, 0x21800000, v220
	v_max_f32_e32 v221, 0x21800000, v221
	v_max_f32_e32 v218, 0x21800000, v218
	v_max_f32_e32 v219, 0x21800000, v219
	v_rcp_f32_e32 v220, v220
	v_rcp_f32_e32 v221, v221
	v_mul_f32_e32 v218, v218, v220
	v_mul_f32_e32 v219, v219, v221
	v_pk_mul_f32 v[22:23], v[22:23], v[218:219]
	v_lshlrev_b32_e32 v242, 16, v151
	v_and_b32_e32 v243, 0xffff0000, v151
	v_lshlrev_b32_e32 v246, 16, v207
	v_and_b32_e32 v247, 0xffff0000, v207
	v_max_f32_e32 v246, 0x21800000, v246
	v_max_f32_e32 v247, 0x21800000, v247
	v_max_f32_e32 v242, 0x21800000, v242
	v_max_f32_e32 v243, 0x21800000, v243
	v_rcp_f32_e32 v246, v246
	v_rcp_f32_e32 v247, v247
	v_mul_f32_e32 v242, v242, v246
	v_mul_f32_e32 v243, v243, v247
	v_pk_mul_f32 v[24:25], v[24:25], v[242:243]
	v_lshlrev_b32_e32 v218, 16, v152
	v_and_b32_e32 v219, 0xffff0000, v152
	v_lshlrev_b32_e32 v220, 16, v208
	v_and_b32_e32 v221, 0xffff0000, v208
	v_max_f32_e32 v220, 0x21800000, v220
	v_max_f32_e32 v221, 0x21800000, v221
	v_max_f32_e32 v218, 0x21800000, v218
	v_max_f32_e32 v219, 0x21800000, v219
	v_rcp_f32_e32 v220, v220
	v_rcp_f32_e32 v221, v221
	v_mul_f32_e32 v218, v218, v220
	v_mul_f32_e32 v219, v219, v221
	v_pk_mul_f32 v[18:19], v[18:19], v[218:219]
	v_lshlrev_b32_e32 v242, 16, v153
	v_and_b32_e32 v243, 0xffff0000, v153
	v_lshlrev_b32_e32 v246, 16, v209
	v_and_b32_e32 v247, 0xffff0000, v209
	v_max_f32_e32 v246, 0x21800000, v246
	v_max_f32_e32 v247, 0x21800000, v247
	v_max_f32_e32 v242, 0x21800000, v242
	v_max_f32_e32 v243, 0x21800000, v243
	v_rcp_f32_e32 v246, v246
	v_rcp_f32_e32 v247, v247
	v_mul_f32_e32 v242, v242, v246
	v_mul_f32_e32 v243, v243, v247
	v_pk_mul_f32 v[20:21], v[20:21], v[242:243]
	s_waitcnt vmcnt(0)
; __device__ __forceinline__ unsigned cvt_pk_bf16(float lo, float hi) { unsigned r; asm volatile("v_cvt_pk_bf16_f32 %0, %1, %2" : "=v"(r) : "v"(lo), "v"(hi)); return r; }
; __device__ __forceinline__ float bf_lo(unsigned w) { return __uint_as_float(w << 16); }
; __device__ __forceinline__ float bf_hi(unsigned w) { return __uint_as_float(w & 0xffff0000u); }
;     __device__ __forceinline__ void operator()(const f32x4 (&acc)[2][2][4][2], const Unit& u, int wr, int wc, int fr, int fq) const {
;     ...
;                 for (int bj = 0; bj < 2; ++bj) { const int row = row0 + ai * HALF + m * 16, col = col0 + bj * HALF; const u32x4 g4 = gv[m][bj];
;                     const f32x4 a0 = acc[ai][bj][m][0], a1 = acc[ai][bj][m][1];
;                     float f0 = a0[0] * bf_lo(g4.x), f1 = a0[1] * bf_hi(g4.x), f2 = a0[2] * bf_lo(g4.y), f3 = a0[3] * bf_hi(g4.y);
;                     float f4 = a1[0] * bf_lo(g4.z), f5 = a1[1] * bf_hi(g4.z), f6 = a1[2] * bf_lo(g4.w), f7 = a1[3] * bf_hi(g4.w);
;                     if (br > 0) {
;                         const unsigned p0 = (unsigned)q0[m][bj], p1 = (unsigned)(q0[m][bj] >> 32), p2 = (unsigned)q1[m][bj], p3 = (unsigned)(q1[m][bj] >> 32);
;                         f0 += bf_lo(p0); f1 += bf_hi(p0); f2 += bf_lo(p1); f3 += bf_hi(p1); f4 += bf_lo(p2); f5 += bf_hi(p2); f6 += bf_lo(p3); f7 += bf_hi(p3);
;                     }
;                     u32x4 w; w.x = cvt_pk_bf16(f0, f1); w.y = cvt_pk_bf16(f2, f3); w.z = cvt_pk_bf16(f4, f5); w.w = cvt_pk_bf16(f6, f7);
;                     *(u32x4*)(Mg + (size_t)row * DM + col) = w; }
	v_lshlrev_b32_e32 v218, 16, v154
	v_and_b32_e32 v219, 0xffff0000, v154
	v_lshlrev_b32_e32 v220, 16, v210
	v_and_b32_e32 v221, 0xffff0000, v210
	v_max_f32_e32 v220, 0x21800000, v220
	v_max_f32_e32 v221, 0x21800000, v221
	v_max_f32_e32 v218, 0x21800000, v218
	v_max_f32_e32 v219, 0x21800000, v219
	v_rcp_f32_e32 v220, v220
	v_rcp_f32_e32 v221, v221
	v_mul_f32_e32 v218, v218, v220
	v_mul_f32_e32 v219, v219, v221
	v_pk_mul_f32 v[14:15], v[14:15], v[218:219]
	v_lshlrev_b32_e32 v242, 16, v155
	v_and_b32_e32 v243, 0xffff0000, v155
	v_lshlrev_b32_e32 v246, 16, v211
	v_and_b32_e32 v247, 0xffff0000, v211
	v_max_f32_e32 v246, 0x21800000, v246
	v_max_f32_e32 v247, 0x21800000, v247
	v_max_f32_e32 v242, 0x21800000, v242
	v_max_f32_e32 v243, 0x21800000, v243
	v_rcp_f32_e32 v246, v246
	v_rcp_f32_e32 v247, v247
	v_mul_f32_e32 v242, v242, v246
	v_mul_f32_e32 v243, v243, v247
	v_pk_mul_f32 v[16:17], v[16:17], v[242:243]
	v_lshlrev_b32_e32 v218, 16, v156
	v_and_b32_e32 v219, 0xffff0000, v156
	v_lshlrev_b32_e32 v220, 16, v212
	v_and_b32_e32 v221, 0xffff0000, v212
	v_max_f32_e32 v220, 0x21800000, v220
	v_max_f32_e32 v221, 0x21800000, v221
	v_max_f32_e32 v218, 0x21800000, v218
	v_max_f32_e32 v219, 0x21800000, v219
	v_rcp_f32_e32 v220, v220
	v_rcp_f32_e32 v221, v221
	v_mul_f32_e32 v218, v218, v220
	v_mul_f32_e32 v219, v219, v221
	v_pk_mul_f32 v[10:11], v[10:11], v[218:219]
	v_lshlrev_b32_e32 v242, 16, v157
	v_and_b32_e32 v243, 0xffff0000, v157
	v_lshlrev_b32_e32 v246, 16, v213
	v_and_b32_e32 v247, 0xffff0000, v213
	v_max_f32_e32 v246, 0x21800000, v246
	v_max_f32_e32 v247, 0x21800000, v247
	v_max_f32_e32 v242, 0x21800000, v242
	v_max_f32_e32 v243, 0x21800000, v243
	v_rcp_f32_e32 v246, v246
	v_rcp_f32_e32 v247, v247
	v_mul_f32_e32 v242, v242, v246
	v_mul_f32_e32 v243, v243, v247
	v_pk_mul_f32 v[12:13], v[12:13], v[242:243]
	v_lshlrev_b32_e32 v218, 16, v158
	v_and_b32_e32 v219, 0xffff0000, v158
	v_lshlrev_b32_e32 v220, 16, v214
	v_and_b32_e32 v221, 0xffff0000, v214
	v_max_f32_e32 v220, 0x21800000, v220
	v_max_f32_e32 v221, 0x21800000, v221
	v_max_f32_e32 v218, 0x21800000, v218
	v_max_f32_e32 v219, 0x21800000, v219
	v_rcp_f32_e32 v220, v220
	v_rcp_f32_e32 v221, v221
	v_mul_f32_e32 v218, v218, v220
	v_mul_f32_e32 v219, v219, v221
	v_pk_mul_f32 v[6:7], v[6:7], v[218:219]
	v_lshlrev_b32_e32 v242, 16, v159
	v_and_b32_e32 v243, 0xffff0000, v159
	v_lshlrev_b32_e32 v246, 16, v215
	v_and_b32_e32 v247, 0xffff0000, v215
	v_max_f32_e32 v246, 0x21800000, v246
	v_max_f32_e32 v247, 0x21800000, v247
	v_max_f32_e32 v242, 0x21800000, v242
	v_max_f32_e32 v243, 0x21800000, v243
	v_rcp_f32_e32 v246, v246
	v_rcp_f32_e32 v247, v247
	v_mul_f32_e32 v242, v242, v246
	v_mul_f32_e32 v243, v243, v247
	v_pk_mul_f32 v[8:9], v[8:9], v[242:243]
	v_lshlrev_b32_e32 v218, 16, v160
	v_and_b32_e32 v219, 0xffff0000, v160
	v_lshlrev_b32_e32 v220, 16, v216
	v_and_b32_e32 v221, 0xffff0000, v216
	v_max_f32_e32 v220, 0x21800000, v220
	v_max_f32_e32 v221, 0x21800000, v221
	v_max_f32_e32 v218, 0x21800000, v218
	v_max_f32_e32 v219, 0x21800000, v219
	v_rcp_f32_e32 v220, v220
	v_rcp_f32_e32 v221, v221
	v_mul_f32_e32 v218, v218, v220
	v_mul_f32_e32 v219, v219, v221
	v_pk_mul_f32 v[2:3], v[2:3], v[218:219]
	v_lshlrev_b32_e32 v242, 16, v161
	v_and_b32_e32 v243, 0xffff0000, v161
	v_lshlrev_b32_e32 v246, 16, v217
	v_and_b32_e32 v247, 0xffff0000, v217
	v_max_f32_e32 v246, 0x21800000, v246
	v_max_f32_e32 v247, 0x21800000, v247
	v_max_f32_e32 v242, 0x21800000, v242
	v_max_f32_e32 v243, 0x21800000, v243
	v_rcp_f32_e32 v246, v246
	v_rcp_f32_e32 v247, v247
	v_mul_f32_e32 v242, v242, v246
	v_mul_f32_e32 v243, v243, v247
	v_pk_mul_f32 v[4:5], v[4:5], v[242:243]
	s_branch .Lrb_tail
.Lrb_final:
	global_load_dwordx4 v[130:133], v[222:223], off
	global_load_dwordx4 v[134:137], v[222:223], off offset:256
	v_lshl_add_u64 v[222:223], v[222:223], 0, s[8:9]
	global_load_dwordx4 v[138:141], v[222:223], off
	global_load_dwordx4 v[142:145], v[222:223], off offset:256
	v_lshl_add_u64 v[222:223], v[222:223], 0, s[8:9]
	global_load_dwordx4 v[146:149], v[222:223], off
	global_load_dwordx4 v[150:153], v[222:223], off offset:256
	v_lshl_add_u64 v[222:223], v[222:223], 0, s[8:9]
	global_load_dwordx4 v[154:157], v[222:223], off
	global_load_dwordx4 v[158:161], v[222:223], off offset:256
	v_lshl_add_u64 v[222:223], v[222:223], 0, s[44:45]
	global_load_dwordx4 v[186:189], v[222:223], off
	global_load_dwordx4 v[190:193], v[222:223], off offset:256
	v_lshl_add_u64 v[222:223], v[222:223], 0, s[8:9]
	global_load_dwordx4 v[194:197], v[222:223], off
	global_load_dwordx4 v[198:201], v[222:223], off offset:256
	v_lshl_add_u64 v[222:223], v[222:223], 0, s[8:9]
	global_load_dwordx4 v[202:205], v[222:223], off
	global_load_dwordx4 v[206:209], v[222:223], off offset:256
	v_lshl_add_u64 v[222:223], v[222:223], 0, s[8:9]
	global_load_dwordx4 v[210:213], v[222:223], off
	global_load_dwordx4 v[214:217], v[222:223], off offset:256
	s_waitcnt vmcnt(15)
	v_lshlrev_b32_e32 v218, 16, v130
	v_and_b32_e32 v219, 0xffff0000, v130
	v_max_f32_e32 v218, 0x21800000, v218
	v_max_f32_e32 v219, 0x21800000, v219
	v_pk_mul_f32 v[126:127], v[126:127], v[218:219]
	v_lshlrev_b32_e32 v242, 16, v131
	v_and_b32_e32 v243, 0xffff0000, v131
	v_max_f32_e32 v242, 0x21800000, v242
	v_max_f32_e32 v243, 0x21800000, v243
	v_pk_mul_f32 v[128:129], v[128:129], v[242:243]
	v_lshlrev_b32_e32 v218, 16, v132
	v_and_b32_e32 v219, 0xffff0000, v132
	v_max_f32_e32 v218, 0x21800000, v218
	v_max_f32_e32 v219, 0x21800000, v219
	v_pk_mul_f32 v[122:123], v[122:123], v[218:219]
	v_lshlrev_b32_e32 v242, 16, v133
	v_and_b32_e32 v243, 0xffff0000, v133
	v_max_f32_e32 v242, 0x21800000, v242
	v_max_f32_e32 v243, 0x21800000, v243
	v_pk_mul_f32 v[124:125], v[124:125], v[242:243]
	v_cvt_pk_bf16_f32 v126, v126, v127
	v_cvt_pk_bf16_f32 v127, v128, v129
	v_cvt_pk_bf16_f32 v128, v122, v123
	v_cvt_pk_bf16_f32 v129, v124, v125
	global_store_dwordx4 v[226:227], v[126:129], off
	s_waitcnt vmcnt(15)
; __device__ __forceinline__ unsigned cvt_pk_bf16(float lo, float hi) { unsigned r; asm volatile("v_cvt_pk_bf16_f32 %0, %1, %2" : "=v"(r) : "v"(lo), "v"(hi)); return r; }
; __device__ __forceinline__ float bf_lo(unsigned w) { return __uint_as_float(w << 16); }
; __device__ __forceinline__ float bf_hi(unsigned w) { return __uint_as_float(w & 0xffff0000u); }
;     __device__ __forceinline__ void operator()(const f32x4 (&acc)[2][2][4][2], const Unit& u, int wr, int wc, int fr, int fq) const {
;     ...
;                 for (int bj = 0; bj < 2; ++bj) { const int row = row0 + ai * HALF + m * 16, col = col0 + bj * HALF; const u32x4 g4 = gv[m][bj];
;                     const f32x4 a0 = acc[ai][bj][m][0], a1 = acc[ai][bj][m][1];
;                     float f0 = a0[0] * bf_lo(g4.x), f1 = a0[1] * bf_hi(g4.x), f2 = a0[2] * bf_lo(g4.y), f3 = a0[3] * bf_hi(g4.y);
;                     float f4 = a1[0] * bf_lo(g4.z), f5 = a1[1] * bf_hi(g4.z), f6 = a1[2] * bf_lo(g4.w), f7 = a1[3] * bf_hi(g4.w);
;                     if (br > 0) {
;                         const unsigned p0 = (unsigned)q0[m][bj], p1 = (unsigned)(q0[m][bj] >> 32), p2 = (unsigned)q1[m][bj], p3 = (unsigned)(q1[m][bj] >> 32);
;                         f0 += bf_lo(p0); f1 += bf_hi(p0); f2 += bf_lo(p1); f3 += bf_hi(p1); f4 += bf_lo(p2); f5 += bf_hi(p2); f6 += bf_lo(p3); f7 += bf_hi(p3);
;                     }
;                     u32x4 w; w.x = cvt_pk_bf16(f0, f1); w.y = cvt_pk_bf16(f2, f3); w.z = cvt_pk_bf16(f4, f5); w.w = cvt_pk_bf16(f6, f7);
;                     *(u32x4*)(Mg + (size_t)row * DM + col) = w; }
	v_lshlrev_b32_e32 v218, 16, v134
	v_and_b32_e32 v219, 0xffff0000, v134
	v_max_f32_e32 v218, 0x21800000, v218
	v_max_f32_e32 v219, 0x21800000, v219
	v_pk_mul_f32 v[118:119], v[118:119], v[218:219]
	v_lshlrev_b32_e32 v242, 16, v135
	v_and_b32_e32 v243, 0xffff0000, v135
	v_max_f32_e32 v242, 0x21800000, v242
	v_max_f32_e32 v243, 0x21800000, v243
	v_pk_mul_f32 v[120:121], v[120:121], v[242:243]
	v_lshlrev_b32_e32 v218, 16, v136
	v_and_b32_e32 v219, 0xffff0000, v136
	v_max_f32_e32 v218, 0x21800000, v218
	v_max_f32_e32 v219, 0x21800000, v219
	v_pk_mul_f32 v[114:115], v[114:115], v[218:219]
	v_lshlrev_b32_e32 v242, 16, v137
	v_and_b32_e32 v243, 0xffff0000, v137
	v_max_f32_e32 v242, 0x21800000, v242
	v_max_f32_e32 v243, 0x21800000, v243
	v_pk_mul_f32 v[116:117], v[116:117], v[242:243]
	v_cvt_pk_bf16_f32 v118, v118, v119
	v_cvt_pk_bf16_f32 v119, v120, v121
	v_cvt_pk_bf16_f32 v120, v114, v115
	v_cvt_pk_bf16_f32 v121, v116, v117
	global_store_dwordx4 v[226:227], v[118:121], off offset:256
	s_waitcnt vmcnt(15)
	v_lshlrev_b32_e32 v218, 16, v138
	v_and_b32_e32 v219, 0xffff0000, v138
	v_max_f32_e32 v218, 0x21800000, v218
	v_max_f32_e32 v219, 0x21800000, v219
	v_pk_mul_f32 v[110:111], v[110:111], v[218:219]
	v_lshlrev_b32_e32 v242, 16, v139
	v_and_b32_e32 v243, 0xffff0000, v139
	v_max_f32_e32 v242, 0x21800000, v242
	v_max_f32_e32 v243, 0x21800000, v243
	v_pk_mul_f32 v[112:113], v[112:113], v[242:243]
	v_lshlrev_b32_e32 v218, 16, v140
	v_and_b32_e32 v219, 0xffff0000, v140
	v_max_f32_e32 v218, 0x21800000, v218
	v_max_f32_e32 v219, 0x21800000, v219
	v_pk_mul_f32 v[106:107], v[106:107], v[218:219]
	v_lshlrev_b32_e32 v242, 16, v141
	v_and_b32_e32 v243, 0xffff0000, v141
	v_max_f32_e32 v242, 0x21800000, v242
	v_max_f32_e32 v243, 0x21800000, v243
	v_pk_mul_f32 v[108:109], v[108:109], v[242:243]
	v_cvt_pk_bf16_f32 v110, v110, v111
	v_cvt_pk_bf16_f32 v111, v112, v113
	v_cvt_pk_bf16_f32 v112, v106, v107
	v_cvt_pk_bf16_f32 v113, v108, v109
	v_lshl_add_u64 v[226:227], v[226:227], 0, s[46:47]
	global_store_dwordx4 v[226:227], v[110:113], off
	s_waitcnt vmcnt(15)
	v_lshlrev_b32_e32 v218, 16, v142
	v_and_b32_e32 v219, 0xffff0000, v142
	v_max_f32_e32 v218, 0x21800000, v218
	v_max_f32_e32 v219, 0x21800000, v219
	v_pk_mul_f32 v[102:103], v[102:103], v[218:219]
	v_lshlrev_b32_e32 v242, 16, v143
	v_and_b32_e32 v243, 0xffff0000, v143
	v_max_f32_e32 v242, 0x21800000, v242
	v_max_f32_e32 v243, 0x21800000, v243
	v_pk_mul_f32 v[104:105], v[104:105], v[242:243]
	v_lshlrev_b32_e32 v218, 16, v144
	v_and_b32_e32 v219, 0xffff0000, v144
	v_max_f32_e32 v218, 0x21800000, v218
	v_max_f32_e32 v219, 0x21800000, v219
	v_pk_mul_f32 v[98:99], v[98:99], v[218:219]
	v_lshlrev_b32_e32 v242, 16, v145
	v_and_b32_e32 v243, 0xffff0000, v145
	v_max_f32_e32 v242, 0x21800000, v242
	v_max_f32_e32 v243, 0x21800000, v243
	v_pk_mul_f32 v[100:101], v[100:101], v[242:243]
	v_cvt_pk_bf16_f32 v102, v102, v103
	v_cvt_pk_bf16_f32 v103, v104, v105
	v_cvt_pk_bf16_f32 v104, v98, v99
	v_cvt_pk_bf16_f32 v105, v100, v101
	global_store_dwordx4 v[226:227], v[102:105], off offset:256
	s_waitcnt vmcnt(15)
	v_lshlrev_b32_e32 v218, 16, v146
	v_and_b32_e32 v219, 0xffff0000, v146
	v_max_f32_e32 v218, 0x21800000, v218
	v_max_f32_e32 v219, 0x21800000, v219
	v_pk_mul_f32 v[94:95], v[94:95], v[218:219]
	v_lshlrev_b32_e32 v242, 16, v147
	v_and_b32_e32 v243, 0xffff0000, v147
	v_max_f32_e32 v242, 0x21800000, v242
	v_max_f32_e32 v243, 0x21800000, v243
	v_pk_mul_f32 v[96:97], v[96:97], v[242:243]
	v_lshlrev_b32_e32 v218, 16, v148
	v_and_b32_e32 v219, 0xffff0000, v148
	v_max_f32_e32 v218, 0x21800000, v218
	v_max_f32_e32 v219, 0x21800000, v219
	v_pk_mul_f32 v[90:91], v[90:91], v[218:219]
	v_lshlrev_b32_e32 v242, 16, v149
	v_and_b32_e32 v243, 0xffff0000, v149
	v_max_f32_e32 v242, 0x21800000, v242
	v_max_f32_e32 v243, 0x21800000, v243
	v_pk_mul_f32 v[92:93], v[92:93], v[242:243]
	v_cvt_pk_bf16_f32 v94, v94, v95
	v_cvt_pk_bf16_f32 v95, v96, v97
	v_cvt_pk_bf16_f32 v96, v90, v91
	v_cvt_pk_bf16_f32 v97, v92, v93
	v_lshl_add_u64 v[226:227], v[226:227], 0, s[46:47]
	global_store_dwordx4 v[226:227], v[94:97], off
	s_waitcnt vmcnt(15)
	v_lshlrev_b32_e32 v218, 16, v150
	v_and_b32_e32 v219, 0xffff0000, v150
	v_max_f32_e32 v218, 0x21800000, v218
	v_max_f32_e32 v219, 0x21800000, v219
	v_pk_mul_f32 v[86:87], v[86:87], v[218:219]
	v_lshlrev_b32_e32 v242, 16, v151
	v_and_b32_e32 v243, 0xffff0000, v151
	v_max_f32_e32 v242, 0x21800000, v242
	v_max_f32_e32 v243, 0x21800000, v243
	v_pk_mul_f32 v[88:89], v[88:89], v[242:243]
	v_lshlrev_b32_e32 v218, 16, v152
	v_and_b32_e32 v219, 0xffff0000, v152
	v_max_f32_e32 v218, 0x21800000, v218
	v_max_f32_e32 v219, 0x21800000, v219
	v_pk_mul_f32 v[82:83], v[82:83], v[218:219]
	v_lshlrev_b32_e32 v242, 16, v153
	v_and_b32_e32 v243, 0xffff0000, v153
	v_max_f32_e32 v242, 0x21800000, v242
	v_max_f32_e32 v243, 0x21800000, v243
	v_pk_mul_f32 v[84:85], v[84:85], v[242:243]
	v_cvt_pk_bf16_f32 v86, v86, v87
	v_cvt_pk_bf16_f32 v87, v88, v89
	v_cvt_pk_bf16_f32 v88, v82, v83
	v_cvt_pk_bf16_f32 v89, v84, v85
	global_store_dwordx4 v[226:227], v[86:89], off offset:256
	s_waitcnt vmcnt(15)
	v_lshlrev_b32_e32 v218, 16, v154
	v_and_b32_e32 v219, 0xffff0000, v154
	v_max_f32_e32 v218, 0x21800000, v218
	v_max_f32_e32 v219, 0x21800000, v219
	v_pk_mul_f32 v[78:79], v[78:79], v[218:219]
	v_lshlrev_b32_e32 v242, 16, v155
	v_and_b32_e32 v243, 0xffff0000, v155
	v_max_f32_e32 v242, 0x21800000, v242
	v_max_f32_e32 v243, 0x21800000, v243
	v_pk_mul_f32 v[80:81], v[80:81], v[242:243]
	v_lshlrev_b32_e32 v218, 16, v156
	v_and_b32_e32 v219, 0xffff0000, v156
	v_max_f32_e32 v218, 0x21800000, v218
	v_max_f32_e32 v219, 0x21800000, v219
	v_pk_mul_f32 v[74:75], v[74:75], v[218:219]
	v_lshlrev_b32_e32 v242, 16, v157
	v_and_b32_e32 v243, 0xffff0000, v157
	v_max_f32_e32 v242, 0x21800000, v242
	v_max_f32_e32 v243, 0x21800000, v243
	v_pk_mul_f32 v[76:77], v[76:77], v[242:243]
	v_cvt_pk_bf16_f32 v78, v78, v79
	v_cvt_pk_bf16_f32 v79, v80, v81
	v_cvt_pk_bf16_f32 v80, v74, v75
	v_cvt_pk_bf16_f32 v81, v76, v77
	v_lshl_add_u64 v[226:227], v[226:227], 0, s[46:47]
	global_store_dwordx4 v[226:227], v[78:81], off
	s_waitcnt vmcnt(15)
; __device__ __forceinline__ unsigned cvt_pk_bf16(float lo, float hi) { unsigned r; asm volatile("v_cvt_pk_bf16_f32 %0, %1, %2" : "=v"(r) : "v"(lo), "v"(hi)); return r; }
; __device__ __forceinline__ float bf_lo(unsigned w) { return __uint_as_float(w << 16); }
; __device__ __forceinline__ float bf_hi(unsigned w) { return __uint_as_float(w & 0xffff0000u); }
;     __device__ __forceinline__ void operator()(const f32x4 (&acc)[2][2][4][2], const Unit& u, int wr, int wc, int fr, int fq) const {
;     ...
;                 for (int bj = 0; bj < 2; ++bj) { const int row = row0 + ai * HALF + m * 16, col = col0 + bj * HALF; const u32x4 g4 = gv[m][bj];
;                     const f32x4 a0 = acc[ai][bj][m][0], a1 = acc[ai][bj][m][1];
;                     float f0 = a0[0] * bf_lo(g4.x), f1 = a0[1] * bf_hi(g4.x), f2 = a0[2] * bf_lo(g4.y), f3 = a0[3] * bf_hi(g4.y);
;                     float f4 = a1[0] * bf_lo(g4.z), f5 = a1[1] * bf_hi(g4.z), f6 = a1[2] * bf_lo(g4.w), f7 = a1[3] * bf_hi(g4.w);
;                     if (br > 0) {
;                         const unsigned p0 = (unsigned)q0[m][bj], p1 = (unsigned)(q0[m][bj] >> 32), p2 = (unsigned)q1[m][bj], p3 = (unsigned)(q1[m][bj] >> 32);
;                         f0 += bf_lo(p0); f1 += bf_hi(p0); f2 += bf_lo(p1); f3 += bf_hi(p1); f4 += bf_lo(p2); f5 += bf_hi(p2); f6 += bf_lo(p3); f7 += bf_hi(p3);
;                     }
;                     u32x4 w; w.x = cvt_pk_bf16(f0, f1); w.y = cvt_pk_bf16(f2, f3); w.z = cvt_pk_bf16(f4, f5); w.w = cvt_pk_bf16(f6, f7);
;                     *(u32x4*)(Mg + (size_t)row * DM + col) = w; }
	v_lshlrev_b32_e32 v218, 16, v158
	v_and_b32_e32 v219, 0xffff0000, v158
	v_max_f32_e32 v218, 0x21800000, v218
	v_max_f32_e32 v219, 0x21800000, v219
	v_pk_mul_f32 v[70:71], v[70:71], v[218:219]
	v_lshlrev_b32_e32 v242, 16, v159
	v_and_b32_e32 v243, 0xffff0000, v159
	v_max_f32_e32 v242, 0x21800000, v242
	v_max_f32_e32 v243, 0x21800000, v243
	v_pk_mul_f32 v[72:73], v[72:73], v[242:243]
	v_lshlrev_b32_e32 v218, 16, v160
	v_and_b32_e32 v219, 0xffff0000, v160
	v_max_f32_e32 v218, 0x21800000, v218
	v_max_f32_e32 v219, 0x21800000, v219
	v_pk_mul_f32 v[66:67], v[66:67], v[218:219]
	v_lshlrev_b32_e32 v242, 16, v161
	v_and_b32_e32 v243, 0xffff0000, v161
	v_max_f32_e32 v242, 0x21800000, v242
	v_max_f32_e32 v243, 0x21800000, v243
	v_pk_mul_f32 v[68:69], v[68:69], v[242:243]
	v_cvt_pk_bf16_f32 v70, v70, v71
	v_cvt_pk_bf16_f32 v71, v72, v73
	v_cvt_pk_bf16_f32 v72, v66, v67
	v_cvt_pk_bf16_f32 v73, v68, v69
	global_store_dwordx4 v[226:227], v[70:73], off offset:256
	v_lshl_add_u64 v[226:227], v[226:227], 0, s[42:43]
	s_waitcnt vmcnt(15)
	v_lshlrev_b32_e32 v218, 16, v186
	v_and_b32_e32 v219, 0xffff0000, v186
	v_max_f32_e32 v218, 0x21800000, v218
	v_max_f32_e32 v219, 0x21800000, v219
	v_pk_mul_f32 v[62:63], v[62:63], v[218:219]
	v_lshlrev_b32_e32 v242, 16, v187
	v_and_b32_e32 v243, 0xffff0000, v187
	v_max_f32_e32 v242, 0x21800000, v242
	v_max_f32_e32 v243, 0x21800000, v243
	v_pk_mul_f32 v[64:65], v[64:65], v[242:243]
	v_lshlrev_b32_e32 v218, 16, v188
	v_and_b32_e32 v219, 0xffff0000, v188
	v_max_f32_e32 v218, 0x21800000, v218
	v_max_f32_e32 v219, 0x21800000, v219
	v_pk_mul_f32 v[58:59], v[58:59], v[218:219]
	v_lshlrev_b32_e32 v242, 16, v189
	v_and_b32_e32 v243, 0xffff0000, v189
	v_max_f32_e32 v242, 0x21800000, v242
	v_max_f32_e32 v243, 0x21800000, v243
	v_pk_mul_f32 v[60:61], v[60:61], v[242:243]
	v_cvt_pk_bf16_f32 v62, v62, v63
	v_cvt_pk_bf16_f32 v63, v64, v65
	v_cvt_pk_bf16_f32 v64, v58, v59
	v_cvt_pk_bf16_f32 v65, v60, v61
	global_store_dwordx4 v[226:227], v[62:65], off
	s_waitcnt vmcnt(15)
	v_lshlrev_b32_e32 v218, 16, v190
	v_and_b32_e32 v219, 0xffff0000, v190
	v_max_f32_e32 v218, 0x21800000, v218
	v_max_f32_e32 v219, 0x21800000, v219
	v_pk_mul_f32 v[54:55], v[54:55], v[218:219]
	v_lshlrev_b32_e32 v242, 16, v191
	v_and_b32_e32 v243, 0xffff0000, v191
	v_max_f32_e32 v242, 0x21800000, v242
	v_max_f32_e32 v243, 0x21800000, v243
	v_pk_mul_f32 v[56:57], v[56:57], v[242:243]
	v_lshlrev_b32_e32 v218, 16, v192
	v_and_b32_e32 v219, 0xffff0000, v192
	v_max_f32_e32 v218, 0x21800000, v218
	v_max_f32_e32 v219, 0x21800000, v219
	v_pk_mul_f32 v[50:51], v[50:51], v[218:219]
	v_lshlrev_b32_e32 v242, 16, v193
	v_and_b32_e32 v243, 0xffff0000, v193
	v_max_f32_e32 v242, 0x21800000, v242
	v_max_f32_e32 v243, 0x21800000, v243
	v_pk_mul_f32 v[52:53], v[52:53], v[242:243]
	v_cvt_pk_bf16_f32 v54, v54, v55
	v_cvt_pk_bf16_f32 v55, v56, v57
	v_cvt_pk_bf16_f32 v56, v50, v51
	v_cvt_pk_bf16_f32 v57, v52, v53
	global_store_dwordx4 v[226:227], v[54:57], off offset:256
	s_waitcnt vmcnt(15)
	v_lshlrev_b32_e32 v218, 16, v194
	v_and_b32_e32 v219, 0xffff0000, v194
	v_max_f32_e32 v218, 0x21800000, v218
	v_max_f32_e32 v219, 0x21800000, v219
	v_pk_mul_f32 v[46:47], v[46:47], v[218:219]
	v_lshlrev_b32_e32 v242, 16, v195
	v_and_b32_e32 v243, 0xffff0000, v195
	v_max_f32_e32 v242, 0x21800000, v242
	v_max_f32_e32 v243, 0x21800000, v243
	v_pk_mul_f32 v[48:49], v[48:49], v[242:243]
	v_lshlrev_b32_e32 v218, 16, v196
	v_and_b32_e32 v219, 0xffff0000, v196
	v_max_f32_e32 v218, 0x21800000, v218
	v_max_f32_e32 v219, 0x21800000, v219
	v_pk_mul_f32 v[42:43], v[42:43], v[218:219]
	v_lshlrev_b32_e32 v242, 16, v197
	v_and_b32_e32 v243, 0xffff0000, v197
	v_max_f32_e32 v242, 0x21800000, v242
	v_max_f32_e32 v243, 0x21800000, v243
	v_pk_mul_f32 v[44:45], v[44:45], v[242:243]
	v_cvt_pk_bf16_f32 v46, v46, v47
	v_cvt_pk_bf16_f32 v47, v48, v49
	v_cvt_pk_bf16_f32 v48, v42, v43
	v_cvt_pk_bf16_f32 v49, v44, v45
	v_lshl_add_u64 v[226:227], v[226:227], 0, s[46:47]
	global_store_dwordx4 v[226:227], v[46:49], off
	s_waitcnt vmcnt(15)
; __device__ __forceinline__ unsigned cvt_pk_bf16(float lo, float hi) { unsigned r; asm volatile("v_cvt_pk_bf16_f32 %0, %1, %2" : "=v"(r) : "v"(lo), "v"(hi)); return r; }
; __device__ __forceinline__ float bf_lo(unsigned w) { return __uint_as_float(w << 16); }
; __device__ __forceinline__ float bf_hi(unsigned w) { return __uint_as_float(w & 0xffff0000u); }
;     __device__ __forceinline__ void operator()(const f32x4 (&acc)[2][2][4][2], const Unit& u, int wr, int wc, int fr, int fq) const {
;     ...
;                 for (int bj = 0; bj < 2; ++bj) { const int row = row0 + ai * HALF + m * 16, col = col0 + bj * HALF; const u32x4 g4 = gv[m][bj];
;                     const f32x4 a0 = acc[ai][bj][m][0], a1 = acc[ai][bj][m][1];
;                     float f0 = a0[0] * bf_lo(g4.x), f1 = a0[1] * bf_hi(g4.x), f2 = a0[2] * bf_lo(g4.y), f3 = a0[3] * bf_hi(g4.y);
;                     float f4 = a1[0] * bf_lo(g4.z), f5 = a1[1] * bf_hi(g4.z), f6 = a1[2] * bf_lo(g4.w), f7 = a1[3] * bf_hi(g4.w);
;                     if (br > 0) {
;                         const unsigned p0 = (unsigned)q0[m][bj], p1 = (unsigned)(q0[m][bj] >> 32), p2 = (unsigned)q1[m][bj], p3 = (unsigned)(q1[m][bj] >> 32);
;                         f0 += bf_lo(p0); f1 += bf_hi(p0); f2 += bf_lo(p1); f3 += bf_hi(p1); f4 += bf_lo(p2); f5 += bf_hi(p2); f6 += bf_lo(p3); f7 += bf_hi(p3);
;                     }
;                     u32x4 w; w.x = cvt_pk_bf16(f0, f1); w.y = cvt_pk_bf16(f2, f3); w.z = cvt_pk_bf16(f4, f5); w.w = cvt_pk_bf16(f6, f7);
;                     *(u32x4*)(Mg + (size_t)row * DM + col) = w; }
	v_lshlrev_b32_e32 v218, 16, v198
	v_and_b32_e32 v219, 0xffff0000, v198
	v_max_f32_e32 v218, 0x21800000, v218
	v_max_f32_e32 v219, 0x21800000, v219
	v_pk_mul_f32 v[38:39], v[38:39], v[218:219]
	v_lshlrev_b32_e32 v242, 16, v199
	v_and_b32_e32 v243, 0xffff0000, v199
	v_max_f32_e32 v242, 0x21800000, v242
	v_max_f32_e32 v243, 0x21800000, v243
	v_pk_mul_f32 v[40:41], v[40:41], v[242:243]
	v_lshlrev_b32_e32 v218, 16, v200
	v_and_b32_e32 v219, 0xffff0000, v200
	v_max_f32_e32 v218, 0x21800000, v218
	v_max_f32_e32 v219, 0x21800000, v219
	v_pk_mul_f32 v[34:35], v[34:35], v[218:219]
	v_lshlrev_b32_e32 v242, 16, v201
	v_and_b32_e32 v243, 0xffff0000, v201
	v_max_f32_e32 v242, 0x21800000, v242
	v_max_f32_e32 v243, 0x21800000, v243
	v_pk_mul_f32 v[36:37], v[36:37], v[242:243]
	v_cvt_pk_bf16_f32 v38, v38, v39
	v_cvt_pk_bf16_f32 v39, v40, v41
	v_cvt_pk_bf16_f32 v40, v34, v35
	v_cvt_pk_bf16_f32 v41, v36, v37
	global_store_dwordx4 v[226:227], v[38:41], off offset:256
	s_waitcnt vmcnt(15)
	v_lshlrev_b32_e32 v218, 16, v202
	v_and_b32_e32 v219, 0xffff0000, v202
	v_max_f32_e32 v218, 0x21800000, v218
	v_max_f32_e32 v219, 0x21800000, v219
	v_pk_mul_f32 v[30:31], v[30:31], v[218:219]
	v_lshlrev_b32_e32 v242, 16, v203
	v_and_b32_e32 v243, 0xffff0000, v203
	v_max_f32_e32 v242, 0x21800000, v242
	v_max_f32_e32 v243, 0x21800000, v243
	v_pk_mul_f32 v[32:33], v[32:33], v[242:243]
	v_lshlrev_b32_e32 v218, 16, v204
	v_and_b32_e32 v219, 0xffff0000, v204
	v_max_f32_e32 v218, 0x21800000, v218
	v_max_f32_e32 v219, 0x21800000, v219
	v_pk_mul_f32 v[26:27], v[26:27], v[218:219]
	v_lshlrev_b32_e32 v242, 16, v205
	v_and_b32_e32 v243, 0xffff0000, v205
	v_max_f32_e32 v242, 0x21800000, v242
	v_max_f32_e32 v243, 0x21800000, v243
	v_pk_mul_f32 v[28:29], v[28:29], v[242:243]
	v_cvt_pk_bf16_f32 v30, v30, v31
	v_cvt_pk_bf16_f32 v31, v32, v33
	v_cvt_pk_bf16_f32 v32, v26, v27
	v_cvt_pk_bf16_f32 v33, v28, v29
	v_lshl_add_u64 v[226:227], v[226:227], 0, s[46:47]
	global_store_dwordx4 v[226:227], v[30:33], off
	s_waitcnt vmcnt(15)
	v_lshlrev_b32_e32 v218, 16, v206
	v_and_b32_e32 v219, 0xffff0000, v206
	v_max_f32_e32 v218, 0x21800000, v218
	v_max_f32_e32 v219, 0x21800000, v219
	v_pk_mul_f32 v[22:23], v[22:23], v[218:219]
	v_lshlrev_b32_e32 v242, 16, v207
	v_and_b32_e32 v243, 0xffff0000, v207
	v_max_f32_e32 v242, 0x21800000, v242
	v_max_f32_e32 v243, 0x21800000, v243
	v_pk_mul_f32 v[24:25], v[24:25], v[242:243]
	v_lshlrev_b32_e32 v218, 16, v208
	v_and_b32_e32 v219, 0xffff0000, v208
	v_max_f32_e32 v218, 0x21800000, v218
	v_max_f32_e32 v219, 0x21800000, v219
	v_pk_mul_f32 v[18:19], v[18:19], v[218:219]
	v_lshlrev_b32_e32 v242, 16, v209
	v_and_b32_e32 v243, 0xffff0000, v209
	v_max_f32_e32 v242, 0x21800000, v242
	v_max_f32_e32 v243, 0x21800000, v243
	v_pk_mul_f32 v[20:21], v[20:21], v[242:243]
	v_cvt_pk_bf16_f32 v22, v22, v23
	v_cvt_pk_bf16_f32 v23, v24, v25
	v_cvt_pk_bf16_f32 v24, v18, v19
	v_cvt_pk_bf16_f32 v25, v20, v21
	global_store_dwordx4 v[226:227], v[22:25], off offset:256
	s_waitcnt vmcnt(15)
	v_lshlrev_b32_e32 v218, 16, v210
	v_and_b32_e32 v219, 0xffff0000, v210
	v_max_f32_e32 v218, 0x21800000, v218
	v_max_f32_e32 v219, 0x21800000, v219
	v_pk_mul_f32 v[14:15], v[14:15], v[218:219]
	v_lshlrev_b32_e32 v242, 16, v211
	v_and_b32_e32 v243, 0xffff0000, v211
	v_max_f32_e32 v242, 0x21800000, v242
	v_max_f32_e32 v243, 0x21800000, v243
	v_pk_mul_f32 v[16:17], v[16:17], v[242:243]
	v_lshlrev_b32_e32 v218, 16, v212
	v_and_b32_e32 v219, 0xffff0000, v212
	v_max_f32_e32 v218, 0x21800000, v218
	v_max_f32_e32 v219, 0x21800000, v219
	v_pk_mul_f32 v[10:11], v[10:11], v[218:219]
	v_lshlrev_b32_e32 v242, 16, v213
	v_and_b32_e32 v243, 0xffff0000, v213
	v_max_f32_e32 v242, 0x21800000, v242
	v_max_f32_e32 v243, 0x21800000, v243
	v_pk_mul_f32 v[12:13], v[12:13], v[242:243]
	v_cvt_pk_bf16_f32 v14, v14, v15
	v_cvt_pk_bf16_f32 v15, v16, v17
	v_cvt_pk_bf16_f32 v16, v10, v11
	v_cvt_pk_bf16_f32 v17, v12, v13
	v_lshl_add_u64 v[226:227], v[226:227], 0, s[46:47]
	global_store_dwordx4 v[226:227], v[14:17], off
	s_waitcnt vmcnt(15)
	v_lshlrev_b32_e32 v218, 16, v214
	v_and_b32_e32 v219, 0xffff0000, v214
	v_max_f32_e32 v218, 0x21800000, v218
	v_max_f32_e32 v219, 0x21800000, v219
	v_pk_mul_f32 v[6:7], v[6:7], v[218:219]
	v_lshlrev_b32_e32 v242, 16, v215
	v_and_b32_e32 v243, 0xffff0000, v215
	v_max_f32_e32 v242, 0x21800000, v242
	v_max_f32_e32 v243, 0x21800000, v243
	v_pk_mul_f32 v[8:9], v[8:9], v[242:243]
	v_lshlrev_b32_e32 v218, 16, v216
	v_and_b32_e32 v219, 0xffff0000, v216
	v_max_f32_e32 v218, 0x21800000, v218
	v_max_f32_e32 v219, 0x21800000, v219
	v_pk_mul_f32 v[2:3], v[2:3], v[218:219]
	v_lshlrev_b32_e32 v242, 16, v217
	v_and_b32_e32 v243, 0xffff0000, v217
	v_max_f32_e32 v242, 0x21800000, v242
	v_max_f32_e32 v243, 0x21800000, v243
	v_pk_mul_f32 v[4:5], v[4:5], v[242:243]
	v_cvt_pk_bf16_f32 v6, v6, v7
	v_cvt_pk_bf16_f32 v7, v8, v9
	v_cvt_pk_bf16_f32 v8, v2, v3
	v_cvt_pk_bf16_f32 v9, v4, v5
	global_store_dwordx4 v[226:227], v[6:9], off offset:256

; DI unsigned cvtpk(float lo, float hi) { typedef float f2 __attribute__((ext_vector_type(2))); typedef __bf16 b2 __attribute__((ext_vector_type(2))); f2 v = {lo, hi}; b2 b = __builtin_convertvector(v, b2); return __builtin_bit_cast(unsigned, b); }
; DI void rms_row_bf16(const float* xrow, const float* gam, bf16* orow, int lane) {
;     f32x4 v[8]; float ss = 0.f;
; #pragma unroll
;     for (int j = 0; j < 8; ++j) { v[j] = ((const f32x4*)xrow)[lane + 64 * j]; ss += (v[j].x * v[j].x + v[j].y * v[j].y) + (v[j].z * v[j].z + v[j].w * v[j].w); }
;     const float rinv = rsqrtf(wave_sum(ss, lane) * (1.f / DM) + 1e-6f);
; #pragma unroll
;     for (int j = 0; j < 8; ++j) { const f32x4 g = ((const f32x4*)gam)[lane + 64 * j]; v2u w; w.x = cvtpk(v[j].x * rinv * g.x, v[j].y * rinv * g.y); w.y = cvtpk(v[j].z * rinv * g.z, v[j].w * rinv * g.w); ((v2u*)orow)[lane + 64 * j] = w; }
.LBB0_1433:
	global_load_dwordx4 v[128:131], v[2:3], off
	global_load_dwordx4 v[132:135], v[2:3], off offset:1024
	global_load_dwordx4 v[136:139], v[2:3], off offset:2048
	global_load_dwordx4 v[140:143], v[2:3], off offset:3072
	global_load_dwordx4 v[144:147], v[4:5], off
	global_load_dwordx4 v[148:151], v[4:5], off offset:1024
	global_load_dwordx4 v[152:155], v[4:5], off offset:2048
	global_load_dwordx4 v[156:159], v[4:5], off offset:3072
	global_load_dwordx4 v[96:99], v[14:15], off offset:-4096
	global_load_dwordx4 v[100:103], v[14:15], off offset:-3072
	global_load_dwordx4 v[104:107], v[14:15], off offset:-2048
	global_load_dwordx4 v[108:111], v[14:15], off offset:-1024
	global_load_dwordx4 v[112:115], v[14:15], off offset:0
	global_load_dwordx4 v[116:119], v[14:15], off offset:1024
	global_load_dwordx4 v[120:123], v[14:15], off offset:2048
	global_load_dwordx4 v[124:127], v[14:15], off offset:3072
	s_waitcnt vmcnt(0)
.Lrms_b_loop:
	s_waitcnt vmcnt(8)
	v_mov_b32_e32 v64, v96
	v_mov_b32_e32 v65, v97
	v_mov_b32_e32 v66, v98
	v_mov_b32_e32 v67, v99
	v_mov_b32_e32 v68, v100
	v_mov_b32_e32 v69, v101
	v_mov_b32_e32 v70, v102
	v_mov_b32_e32 v71, v103
	v_mov_b32_e32 v72, v104
	v_mov_b32_e32 v73, v105
	v_mov_b32_e32 v74, v106
	v_mov_b32_e32 v75, v107
	v_mov_b32_e32 v76, v108
	v_mov_b32_e32 v77, v109
	v_mov_b32_e32 v78, v110
	v_mov_b32_e32 v79, v111
	v_mov_b32_e32 v80, v112
	v_mov_b32_e32 v81, v113
	v_mov_b32_e32 v82, v114
	v_mov_b32_e32 v83, v115
	v_mov_b32_e32 v84, v116
	v_mov_b32_e32 v85, v117
	v_mov_b32_e32 v86, v118
	v_mov_b32_e32 v87, v119
	v_mov_b32_e32 v88, v120
	v_mov_b32_e32 v89, v121
	v_mov_b32_e32 v90, v122
	v_mov_b32_e32 v91, v123
	v_mov_b32_e32 v92, v124
	v_mov_b32_e32 v93, v125
	v_mov_b32_e32 v94, v126
	v_mov_b32_e32 v95, v127
	s_add_i32 s16, s16, s30
	s_cmpk_gt_i32 s16, 0x3fff
	s_cbranch_scc1 .Lrms_b_nopf
	v_lshl_add_u64 v[14:15], v[14:15], 0, s[60:61]
	global_load_dwordx4 v[96:99], v[14:15], off offset:-4096
	global_load_dwordx4 v[100:103], v[14:15], off offset:-3072
	global_load_dwordx4 v[104:107], v[14:15], off offset:-2048
	global_load_dwordx4 v[108:111], v[14:15], off offset:-1024
	global_load_dwordx4 v[112:115], v[14:15], off offset:0
	global_load_dwordx4 v[116:119], v[14:15], off offset:1024
	global_load_dwordx4 v[120:123], v[14:15], off offset:2048
	global_load_dwordx4 v[124:127], v[14:15], off offset:3072
; DI unsigned cvtpk(float lo, float hi) { typedef float f2 __attribute__((ext_vector_type(2))); typedef __bf16 b2 __attribute__((ext_vector_type(2))); f2 v = {lo, hi}; b2 b = __builtin_convertvector(v, b2); return __builtin_bit_cast(unsigned, b); }
; DI void rms_row_bf16(const float* xrow, const float* gam, bf16* orow, int lane) {
;     f32x4 v[8]; float ss = 0.f;
; #pragma unroll
;     for (int j = 0; j < 8; ++j) { v[j] = ((const f32x4*)xrow)[lane + 64 * j]; ss += (v[j].x * v[j].x + v[j].y * v[j].y) + (v[j].z * v[j].z + v[j].w * v[j].w); }
;     const float rinv = rsqrtf(wave_sum(ss, lane) * (1.f / DM) + 1e-6f);
; #pragma unroll
;     for (int j = 0; j < 8; ++j) { const f32x4 g = ((const f32x4*)gam)[lane + 64 * j]; v2u w; w.x = cvtpk(v[j].x * rinv * g.x, v[j].y * rinv * g.y); w.y = cvtpk(v[j].z * rinv * g.z, v[j].w * rinv * g.w); ((v2u*)orow)[lane + 64 * j] = w; }
; }
.Lrms_b_nopf:
	v_mul_f32_e32 v177, v64, v64
	v_mul_f32_e32 v178, v66, v66
	v_fmac_f32_e32 v177, v65, v65
	v_fmac_f32_e32 v178, v67, v67
	v_add_f32_e32 v176, v177, v178
	v_mul_f32_e32 v177, v68, v68
	v_mul_f32_e32 v178, v70, v70
	v_fmac_f32_e32 v177, v69, v69
	v_fmac_f32_e32 v178, v71, v71
	v_add_f32_e32 v177, v177, v178
	v_add_f32_e32 v176, v176, v177
	v_mul_f32_e32 v177, v72, v72
	v_mul_f32_e32 v178, v74, v74
	v_fmac_f32_e32 v177, v73, v73
	v_fmac_f32_e32 v178, v75, v75
	v_add_f32_e32 v177, v177, v178
	v_add_f32_e32 v176, v176, v177
	v_mul_f32_e32 v177, v76, v76
	v_mul_f32_e32 v178, v78, v78
	v_fmac_f32_e32 v177, v77, v77
	v_fmac_f32_e32 v178, v79, v79
	v_add_f32_e32 v177, v177, v178
	v_add_f32_e32 v176, v176, v177
	v_mul_f32_e32 v177, v80, v80
	v_mul_f32_e32 v178, v82, v82
	v_fmac_f32_e32 v177, v81, v81
	v_fmac_f32_e32 v178, v83, v83
	v_add_f32_e32 v177, v177, v178
	v_add_f32_e32 v176, v176, v177
	v_mul_f32_e32 v177, v84, v84
	v_mul_f32_e32 v178, v86, v86
	v_fmac_f32_e32 v177, v85, v85
	v_fmac_f32_e32 v178, v87, v87
	v_add_f32_e32 v177, v177, v178
	v_add_f32_e32 v176, v176, v177
	v_mul_f32_e32 v177, v88, v88
	v_mul_f32_e32 v178, v90, v90
	v_fmac_f32_e32 v177, v89, v89
	v_fmac_f32_e32 v178, v91, v91
	v_add_f32_e32 v177, v177, v178
	v_add_f32_e32 v176, v176, v177
	v_mul_f32_e32 v177, v92, v92
	v_mul_f32_e32 v178, v94, v94
	v_fmac_f32_e32 v177, v93, v93
	v_fmac_f32_e32 v178, v95, v95
	v_add_f32_e32 v177, v177, v178
	v_add_f32_e32 v176, v176, v177
	ds_bpermute_b32 v179, v0, v176
	s_waitcnt lgkmcnt(0)
	v_add_f32_e32 v176, v176, v179
	ds_bpermute_b32 v179, v16, v176
	s_waitcnt lgkmcnt(0)
	v_add_f32_e32 v176, v176, v179
	ds_bpermute_b32 v179, v17, v176
	s_waitcnt lgkmcnt(0)
	v_add_f32_e32 v176, v176, v179
	ds_bpermute_b32 v179, v18, v176
	s_waitcnt lgkmcnt(0)
	v_add_f32_e32 v176, v176, v179
	ds_bpermute_b32 v179, v19, v176
	s_waitcnt lgkmcnt(0)
	v_add_f32_e32 v176, v176, v179
	ds_bpermute_b32 v179, v20, v176
	s_waitcnt lgkmcnt(0)
	v_add_f32_e32 v176, v176, v179
	v_fmamk_f32 v176, v176, 0x3a000000, v230
	v_mul_f32_e32 v179, 0x4b800000, v176
	v_cmp_gt_f32_e32 vcc, s29, v176
	s_nop 1
	v_cndmask_b32_e32 v176, v176, v179, vcc
	v_rsq_f32_e32 v176, v176
	s_nop 0
	v_mul_f32_e32 v179, 0x45800000, v176
	v_cndmask_b32_e32 v180, v176, v179, vcc
	v_pk_mul_f32 v[64:65], v[64:65], v[180:181] op_sel_hi:[1,0]
	v_pk_mul_f32 v[66:67], v[66:67], v[180:181] op_sel_hi:[1,0]
	v_pk_mul_f32 v[64:65], v[128:129], v[64:65]
	v_pk_mul_f32 v[66:67], v[130:131], v[66:67]
	v_cvt_pk_bf16_f32 v182, v64, v65
	v_cvt_pk_bf16_f32 v183, v66, v67
	global_store_dwordx2 v[12:13], v[182:183], off
	v_pk_mul_f32 v[68:69], v[68:69], v[180:181] op_sel_hi:[1,0]
	v_pk_mul_f32 v[70:71], v[70:71], v[180:181] op_sel_hi:[1,0]
	v_pk_mul_f32 v[68:69], v[132:133], v[68:69]
	v_pk_mul_f32 v[70:71], v[134:135], v[70:71]
	v_cvt_pk_bf16_f32 v184, v68, v69
	v_cvt_pk_bf16_f32 v185, v70, v71
	global_store_dwordx2 v[12:13], v[184:185], off offset:512
	v_pk_mul_f32 v[72:73], v[72:73], v[180:181] op_sel_hi:[1,0]
	v_pk_mul_f32 v[74:75], v[74:75], v[180:181] op_sel_hi:[1,0]
	v_pk_mul_f32 v[72:73], v[136:137], v[72:73]
	v_pk_mul_f32 v[74:75], v[138:139], v[74:75]
	v_cvt_pk_bf16_f32 v182, v72, v73
	v_cvt_pk_bf16_f32 v183, v74, v75
	global_store_dwordx2 v[12:13], v[182:183], off offset:1024
	v_pk_mul_f32 v[76:77], v[76:77], v[180:181] op_sel_hi:[1,0]
	v_pk_mul_f32 v[78:79], v[78:79], v[180:181] op_sel_hi:[1,0]
	v_pk_mul_f32 v[76:77], v[140:141], v[76:77]
	v_pk_mul_f32 v[78:79], v[142:143], v[78:79]
	v_cvt_pk_bf16_f32 v184, v76, v77
	v_cvt_pk_bf16_f32 v185, v78, v79
	global_store_dwordx2 v[12:13], v[184:185], off offset:1536
	v_pk_mul_f32 v[80:81], v[80:81], v[180:181] op_sel_hi:[1,0]
	v_pk_mul_f32 v[82:83], v[82:83], v[180:181] op_sel_hi:[1,0]
	v_pk_mul_f32 v[80:81], v[144:145], v[80:81]
	v_pk_mul_f32 v[82:83], v[146:147], v[82:83]
	v_cvt_pk_bf16_f32 v182, v80, v81
	v_cvt_pk_bf16_f32 v183, v82, v83
	global_store_dwordx2 v[12:13], v[182:183], off offset:2048
	v_pk_mul_f32 v[84:85], v[84:85], v[180:181] op_sel_hi:[1,0]
	v_pk_mul_f32 v[86:87], v[86:87], v[180:181] op_sel_hi:[1,0]
	v_pk_mul_f32 v[84:85], v[148:149], v[84:85]
	v_pk_mul_f32 v[86:87], v[150:151], v[86:87]
	v_cvt_pk_bf16_f32 v184, v84, v85
	v_cvt_pk_bf16_f32 v185, v86, v87
	global_store_dwordx2 v[12:13], v[184:185], off offset:2560
	v_pk_mul_f32 v[88:89], v[88:89], v[180:181] op_sel_hi:[1,0]
	v_pk_mul_f32 v[90:91], v[90:91], v[180:181] op_sel_hi:[1,0]
	v_pk_mul_f32 v[88:89], v[152:153], v[88:89]
	v_pk_mul_f32 v[90:91], v[154:155], v[90:91]
	v_cvt_pk_bf16_f32 v182, v88, v89
	v_cvt_pk_bf16_f32 v183, v90, v91
	global_store_dwordx2 v[12:13], v[182:183], off offset:3072
	v_pk_mul_f32 v[92:93], v[92:93], v[180:181] op_sel_hi:[1,0]
	v_pk_mul_f32 v[94:95], v[94:95], v[180:181] op_sel_hi:[1,0]
	v_pk_mul_f32 v[92:93], v[156:157], v[92:93]
	v_pk_mul_f32 v[94:95], v[158:159], v[94:95]
	v_cvt_pk_bf16_f32 v184, v92, v93
	v_cvt_pk_bf16_f32 v185, v94, v95
	global_store_dwordx2 v[12:13], v[184:185], off offset:3584
	v_lshl_add_u64 v[12:13], v[12:13], 0, s[58:59]
	s_cmpk_gt_i32 s16, 0x3fff
	s_cbranch_scc0 .Lrms_b_loop

; DI void rms_row_f32(float* xrow, const float* gam, int lane) {
;     f32x4 v[8]; float ss = 0.f;
; #pragma unroll
;     for (int j = 0; j < 8; ++j) { v[j] = ((const f32x4*)xrow)[lane + 64 * j]; ss += (v[j].x * v[j].x + v[j].y * v[j].y) + (v[j].z * v[j].z + v[j].w * v[j].w); }
;     const float rinv = rsqrtf(wave_sum(ss, lane) * (1.f / DM) + 1e-6f);
; #pragma unroll
;     for (int j = 0; j < 8; ++j) { const f32x4 g = ((const f32x4*)gam)[lane + 64 * j]; ((f32x4*)xrow)[lane + 64 * j] = v[j] * rinv * g; }
; }
.LBB0_1438:
	global_load_dwordx4 v[128:131], v[6:7], off
	global_load_dwordx4 v[132:135], v[6:7], off offset:1024
	global_load_dwordx4 v[136:139], v[6:7], off offset:2048
	global_load_dwordx4 v[140:143], v[6:7], off offset:3072
	global_load_dwordx4 v[144:147], v[8:9], off
	global_load_dwordx4 v[148:151], v[8:9], off offset:1024
	global_load_dwordx4 v[152:155], v[8:9], off offset:2048
	global_load_dwordx4 v[156:159], v[8:9], off offset:3072
	global_load_dwordx4 v[96:99], v[16:17], off offset:-4096
	global_load_dwordx4 v[100:103], v[16:17], off offset:-3072
	global_load_dwordx4 v[104:107], v[16:17], off offset:-2048
	global_load_dwordx4 v[108:111], v[16:17], off offset:-1024
	global_load_dwordx4 v[112:115], v[16:17], off offset:0
	global_load_dwordx4 v[116:119], v[16:17], off offset:1024
	global_load_dwordx4 v[120:123], v[16:17], off offset:2048
	global_load_dwordx4 v[124:127], v[16:17], off offset:3072
	v_mov_b32_e32 v60, v16
	v_mov_b32_e32 v61, v17
	s_waitcnt vmcnt(0)
.Lrms_c_loop:
	s_waitcnt vmcnt(8)
	v_mov_b32_e32 v64, v96
	v_mov_b32_e32 v65, v97
	v_mov_b32_e32 v66, v98
	v_mov_b32_e32 v67, v99
	v_mov_b32_e32 v68, v100
	v_mov_b32_e32 v69, v101
	v_mov_b32_e32 v70, v102
	v_mov_b32_e32 v71, v103
	v_mov_b32_e32 v72, v104
	v_mov_b32_e32 v73, v105
	v_mov_b32_e32 v74, v106
	v_mov_b32_e32 v75, v107
	v_mov_b32_e32 v76, v108
	v_mov_b32_e32 v77, v109
	v_mov_b32_e32 v78, v110
	v_mov_b32_e32 v79, v111
	v_mov_b32_e32 v80, v112
	v_mov_b32_e32 v81, v113
	v_mov_b32_e32 v82, v114
	v_mov_b32_e32 v83, v115
	v_mov_b32_e32 v84, v116
	v_mov_b32_e32 v85, v117
	v_mov_b32_e32 v86, v118
	v_mov_b32_e32 v87, v119
	v_mov_b32_e32 v88, v120
	v_mov_b32_e32 v89, v121
	v_mov_b32_e32 v90, v122
	v_mov_b32_e32 v91, v123
	v_mov_b32_e32 v92, v124
	v_mov_b32_e32 v93, v125
	v_mov_b32_e32 v94, v126
	v_mov_b32_e32 v95, v127
	s_add_i32 s6, s6, s30
	s_cmpk_gt_i32 s6, 0x3fff
	s_cbranch_scc1 .Lrms_c_nopf
	v_lshl_add_u64 v[16:17], v[16:17], 0, s[60:61]
	global_load_dwordx4 v[96:99], v[16:17], off offset:-4096
	global_load_dwordx4 v[100:103], v[16:17], off offset:-3072
	global_load_dwordx4 v[104:107], v[16:17], off offset:-2048
	global_load_dwordx4 v[108:111], v[16:17], off offset:-1024
	global_load_dwordx4 v[112:115], v[16:17], off offset:0
	global_load_dwordx4 v[116:119], v[16:17], off offset:1024
	global_load_dwordx4 v[120:123], v[16:17], off offset:2048
	global_load_dwordx4 v[124:127], v[16:17], off offset:3072
.Lrms_c_nopf:
	v_mul_f32_e32 v177, v64, v64
	v_mul_f32_e32 v178, v66, v66
	v_fmac_f32_e32 v177, v65, v65
	v_fmac_f32_e32 v178, v67, v67
	v_add_f32_e32 v176, v177, v178
	v_mul_f32_e32 v177, v68, v68
	v_mul_f32_e32 v178, v70, v70
	v_fmac_f32_e32 v177, v69, v69
	v_fmac_f32_e32 v178, v71, v71
	v_add_f32_e32 v177, v177, v178
	v_add_f32_e32 v176, v176, v177
	v_mul_f32_e32 v177, v72, v72
	v_mul_f32_e32 v178, v74, v74
	v_fmac_f32_e32 v177, v73, v73
	v_fmac_f32_e32 v178, v75, v75
	v_add_f32_e32 v177, v177, v178
	v_add_f32_e32 v176, v176, v177
	v_mul_f32_e32 v177, v76, v76
	v_mul_f32_e32 v178, v78, v78
	v_fmac_f32_e32 v177, v77, v77
	v_fmac_f32_e32 v178, v79, v79
	v_add_f32_e32 v177, v177, v178
	v_add_f32_e32 v176, v176, v177
	v_mul_f32_e32 v177, v80, v80
	v_mul_f32_e32 v178, v82, v82
	v_fmac_f32_e32 v177, v81, v81
	v_fmac_f32_e32 v178, v83, v83
	v_add_f32_e32 v177, v177, v178
	v_add_f32_e32 v176, v176, v177
	v_mul_f32_e32 v177, v84, v84
	v_mul_f32_e32 v178, v86, v86
	v_fmac_f32_e32 v177, v85, v85
	v_fmac_f32_e32 v178, v87, v87
	v_add_f32_e32 v177, v177, v178
	v_add_f32_e32 v176, v176, v177
	v_mul_f32_e32 v177, v88, v88
	v_mul_f32_e32 v178, v90, v90
	v_fmac_f32_e32 v177, v89, v89
	v_fmac_f32_e32 v178, v91, v91
	v_add_f32_e32 v177, v177, v178
	v_add_f32_e32 v176, v176, v177
	v_mul_f32_e32 v177, v92, v92
	v_mul_f32_e32 v178, v94, v94
	v_fmac_f32_e32 v177, v93, v93
	v_fmac_f32_e32 v178, v95, v95
	v_add_f32_e32 v177, v177, v178
	v_add_f32_e32 v176, v176, v177
	ds_bpermute_b32 v179, v0, v176
	s_waitcnt lgkmcnt(0)
	v_add_f32_e32 v176, v176, v179
	ds_bpermute_b32 v179, v18, v176
	s_waitcnt lgkmcnt(0)
	v_add_f32_e32 v176, v176, v179
	ds_bpermute_b32 v179, v19, v176
	s_waitcnt lgkmcnt(0)
	v_add_f32_e32 v176, v176, v179
	ds_bpermute_b32 v179, v20, v176
	s_waitcnt lgkmcnt(0)
	v_add_f32_e32 v176, v176, v179
	ds_bpermute_b32 v179, v21, v176
	s_waitcnt lgkmcnt(0)
	v_add_f32_e32 v176, v176, v179
	ds_bpermute_b32 v179, v22, v176
	s_waitcnt lgkmcnt(0)
	v_add_f32_e32 v176, v176, v179
	v_fmamk_f32 v176, v176, 0x3a000000, v230
	v_mul_f32_e32 v179, 0x4b800000, v176
	v_cmp_gt_f32_e32 vcc, s29, v176
	s_nop 1
	v_cndmask_b32_e32 v176, v176, v179, vcc
	v_rsq_f32_e32 v176, v176
	s_nop 0
	v_mul_f32_e32 v179, 0x45800000, v176
	v_cndmask_b32_e32 v180, v176, v179, vcc
	v_pk_mul_f32 v[64:65], v[64:65], v[180:181] op_sel_hi:[1,0]
	v_pk_mul_f32 v[66:67], v[66:67], v[180:181] op_sel_hi:[1,0]
	v_pk_mul_f32 v[64:65], v[128:129], v[64:65]
	v_pk_mul_f32 v[66:67], v[130:131], v[66:67]
	global_store_dwordx4 v[60:61], v[64:67], off offset:-4096
	v_pk_mul_f32 v[68:69], v[68:69], v[180:181] op_sel_hi:[1,0]
	v_pk_mul_f32 v[70:71], v[70:71], v[180:181] op_sel_hi:[1,0]
	v_pk_mul_f32 v[68:69], v[132:133], v[68:69]
	v_pk_mul_f32 v[70:71], v[134:135], v[70:71]
	global_store_dwordx4 v[60:61], v[68:71], off offset:-3072
	v_pk_mul_f32 v[72:73], v[72:73], v[180:181] op_sel_hi:[1,0]
	v_pk_mul_f32 v[74:75], v[74:75], v[180:181] op_sel_hi:[1,0]
	v_pk_mul_f32 v[72:73], v[136:137], v[72:73]
	v_pk_mul_f32 v[74:75], v[138:139], v[74:75]
	global_store_dwordx4 v[60:61], v[72:75], off offset:-2048
	v_pk_mul_f32 v[76:77], v[76:77], v[180:181] op_sel_hi:[1,0]
	v_pk_mul_f32 v[78:79], v[78:79], v[180:181] op_sel_hi:[1,0]
	v_pk_mul_f32 v[76:77], v[140:141], v[76:77]
	v_pk_mul_f32 v[78:79], v[142:143], v[78:79]
	global_store_dwordx4 v[60:61], v[76:79], off offset:-1024
	v_pk_mul_f32 v[80:81], v[80:81], v[180:181] op_sel_hi:[1,0]
	v_pk_mul_f32 v[82:83], v[82:83], v[180:181] op_sel_hi:[1,0]
	v_pk_mul_f32 v[80:81], v[144:145], v[80:81]
	v_pk_mul_f32 v[82:83], v[146:147], v[82:83]
	global_store_dwordx4 v[60:61], v[80:83], off offset:0
	v_pk_mul_f32 v[84:85], v[84:85], v[180:181] op_sel_hi:[1,0]
	v_pk_mul_f32 v[86:87], v[86:87], v[180:181] op_sel_hi:[1,0]
	v_pk_mul_f32 v[84:85], v[148:149], v[84:85]
	v_pk_mul_f32 v[86:87], v[150:151], v[86:87]
	global_store_dwordx4 v[60:61], v[84:87], off offset:1024
	v_pk_mul_f32 v[88:89], v[88:89], v[180:181] op_sel_hi:[1,0]
	v_pk_mul_f32 v[90:91], v[90:91], v[180:181] op_sel_hi:[1,0]
	v_pk_mul_f32 v[88:89], v[152:153], v[88:89]
	v_pk_mul_f32 v[90:91], v[154:155], v[90:91]
	global_store_dwordx4 v[60:61], v[88:91], off offset:2048
	v_pk_mul_f32 v[92:93], v[92:93], v[180:181] op_sel_hi:[1,0]
	v_pk_mul_f32 v[94:95], v[94:95], v[180:181] op_sel_hi:[1,0]
	v_pk_mul_f32 v[92:93], v[156:157], v[92:93]
	v_pk_mul_f32 v[94:95], v[158:159], v[94:95]
	global_store_dwordx4 v[60:61], v[92:95], off offset:3072
	v_lshl_add_u64 v[60:61], v[60:61], 0, s[60:61]
	s_cmpk_gt_i32 s6, 0x3fff
	s_cbranch_scc0 .Lrms_c_loop
